# GEMM K-loops restructured to 4 barrier-phases per k-step (32 MFMA per interval), peeled first iteration, ret_out load edits
# baseline (speedup 1.0000x reference)
; #define PG8_STAGE(bufoff, gbase, voff) do { _Pragma("unroll") for (int _i = 0; _i < 2; ++_i) \
;         __builtin_amdgcn_global_load_lds((const unsigned*)((const char*)(gbase) + (voff)[_i]), (LAS unsigned*)(lds + (bufoff) + ldsw + _i * 8192), 16, 0, 0); } while (0)
; #define PG8_LDA(dst, b, h) do { _Pragma("unroll") for (int m = 0; m < 4; ++m) _Pragma("unroll") for (int k = 0; k < 2; ++k) dst[m][k] = *(const LAS bf16x8*)(lds + PG8_SA(b, h) + aoff + m * 2048 + k * 1024); } while (0)
; #define PG8_LDB(dst, b, h) do { _Pragma("unroll") for (int n = 0; n < 2; ++n) _Pragma("unroll") for (int k = 0; k < 2; ++k) dst[n][k] = *(const LAS bf16x8*)(lds + PG8_SB(b, h) + boff + n * 2048 + k * 1024); } while (0)
; #define PG8_MMA(ai, bj, At, Bt) do { __builtin_amdgcn_s_setprio(1); _Pragma("unroll") for (int m = 0; m < 4; ++m) _Pragma("unroll") for (int n = 0; n < 2; ++n) _Pragma("unroll") for (int k = 0; k < 2; ++k) \
;         acc[ai][bj][m][n] = __builtin_amdgcn_mfma_f32_16x16x32_bf16(Bt[n][k], At[m][k], acc[ai][bj][m][n], 0, 0, 0); __builtin_amdgcn_s_setprio(0); } while (0)
; #define PG8_WAIT_L(n) asm volatile("s_waitcnt lgkmcnt(" #n ")" ::: "memory")
; #define PG8_BAR __builtin_amdgcn_s_barrier()
; #define PG8_SCHED __builtin_amdgcn_sched_barrier(0)
; template <class Epi, class Sched>
; __device__ __forceinline__ void gemm_phase(LAS unsigned char* lds, const Gemm g, const Sched& S, const Epi& E, int tid) {
;     ...
;             const char* a1 = cA + (size_t)(t + 1) * kstep;
;             const char* a2 = last ? nA : cA + (size_t)(t + 2) * kstep; const char* b2 = last ? nB : cB + (size_t)(t + 2) * kstep;
;             const char* a3 = a2 + kstep; const char* b3 = b2 + kstep;
;             PG8_LDB(B0, 0, 0); PG8_SCHED; PG8_LDA(At, 0, 0); PG8_STAGE(PG8_SA(1, 1), a1 + hstep, voffA);
;             PG8_WAIT_L(8); PG8_BAR; PG8_WAIT_L(0); PG8_MMA(0, 0, At, B0); PG8_BAR; PG8_SCHED;
;             PG8_LDB(B1, 0, 1); PG8_STAGE(PG8_SB(0, 0), b2, voffB);
;             PG8_BAR; PG8_WAIT_L(0); PG8_MMA(0, 1, At, B1); PG8_BAR;
;             PG8_LDA(At, 0, 1); PG8_STAGE(PG8_SA(0, 0), a2, voffA);
;             PG8_BAR; PG8_WAIT_L(0); PG8_MMA(1, 0, At, B0); PG8_BAR; PG8_SCHED;
;             PG8_STAGE(PG8_SB(0, 1), b2 + hstep, voffB);
.LBB0_99:
	s_add_u32 vcc_lo, s44, 0x80
	s_addc_u32 vcc_hi, s45, 0
	s_add_u32 s96, s34, 0x100
	s_addc_u32 s65, s35, 0
	s_mov_b32 s34, 0
	s_add_i32 s0, s34, 2
	s_add_u32 s1, vcc_lo, 0x80
	s_addc_u32 s35, vcc_hi, 0
	s_add_i32 s17, 0, 0x10000
	v_add_u32_e32 v152, s17, v141
	ds_read_b128 v[144:147], v152
	ds_read_b128 v[148:151], v152 offset:1024
	ds_read_b128 v[160:163], v152 offset:2048
	ds_read_b128 v[164:167], v152 offset:3072
	s_cmp_eq_u32 s95, s34
	s_cselect_b32 s34, s38, s1
	s_cselect_b32 s35, s39, s35
	s_cselect_b32 s45, s41, s65
	s_cselect_b32 s44, s40, s96
	v_lshl_add_u64 v[152:153], vcc, 0, v[134:135]
	s_add_i32 m0, s88, 0xc000
	ds_read_b128 v[168:171], v143
	ds_read_b128 v[184:187], v143 offset:1024
	ds_read_b128 v[188:191], v143 offset:2048
	ds_read_b128 v[192:195], v143 offset:3072
	ds_read_b128 v[196:199], v143 offset:4096
	ds_read_b128 v[200:203], v143 offset:5120
	ds_read_b128 v[204:207], v143 offset:6144
	ds_read_b128 v[208:211], v143 offset:7168
	global_load_lds_dwordx4 v[152:153], off
	v_lshl_add_u64 v[152:153], vcc, 0, v[136:137]
	s_add_i32 m0, s88, 0xe000
	s_nop 0
	global_load_lds_dwordx4 v[152:153], off
	s_add_i32 s1, 0, 0x14000
	v_add_u32_e32 v152, s1, v141
	ds_read_b128 v[212:215], v152
	ds_read_b128 v[216:219], v152 offset:1024
	ds_read_b128 v[220:223], v152 offset:2048
	ds_read_b128 v[224:227], v152 offset:3072
	s_waitcnt lgkmcnt(0)
	s_setprio 1
	s_barrier
	v_mfma_f32_16x16x32_bf16 v[124:127], v[144:147], v[168:171], 0
	v_mfma_f32_16x16x32_bf16 v[120:123], v[160:163], v[168:171], 0
	v_mfma_f32_16x16x32_bf16 v[116:119], v[144:147], v[188:191], 0
	v_mfma_f32_16x16x32_bf16 v[112:115], v[160:163], v[188:191], 0
	v_mfma_f32_16x16x32_bf16 v[100:103], v[144:147], v[196:199], 0
	v_mfma_f32_16x16x32_bf16 v[96:99], v[160:163], v[196:199], 0
	v_mfma_f32_16x16x32_bf16 v[84:87], v[144:147], v[204:207], 0
	v_mfma_f32_16x16x32_bf16 v[80:83], v[160:163], v[204:207], 0
	v_mfma_f32_16x16x32_bf16 v[124:127], v[148:151], v[184:187], v[124:127]
	v_mfma_f32_16x16x32_bf16 v[120:123], v[164:167], v[184:187], v[120:123]
	v_mfma_f32_16x16x32_bf16 v[116:119], v[148:151], v[192:195], v[116:119]
	v_mfma_f32_16x16x32_bf16 v[112:115], v[164:167], v[192:195], v[112:115]
	v_mfma_f32_16x16x32_bf16 v[100:103], v[148:151], v[200:203], v[100:103]
	v_mfma_f32_16x16x32_bf16 v[96:99], v[164:167], v[200:203], v[96:99]
	v_mfma_f32_16x16x32_bf16 v[84:87], v[148:151], v[208:211], v[84:87]
	v_mfma_f32_16x16x32_bf16 v[80:83], v[164:167], v[208:211], v[80:83]
	v_mfma_f32_16x16x32_bf16 v[108:111], v[212:215], v[168:171], 0
	v_mfma_f32_16x16x32_bf16 v[104:107], v[220:223], v[168:171], 0
	v_mfma_f32_16x16x32_bf16 v[92:95], v[212:215], v[188:191], 0
	v_mfma_f32_16x16x32_bf16 v[88:91], v[220:223], v[188:191], 0
	v_mfma_f32_16x16x32_bf16 v[76:79], v[212:215], v[196:199], 0
	v_mfma_f32_16x16x32_bf16 v[72:75], v[220:223], v[196:199], 0
	v_mfma_f32_16x16x32_bf16 v[68:71], v[212:215], v[204:207], 0
	v_mfma_f32_16x16x32_bf16 v[64:67], v[220:223], v[204:207], 0
	v_mfma_f32_16x16x32_bf16 v[108:111], v[216:219], v[184:187], v[108:111]
	v_mfma_f32_16x16x32_bf16 v[104:107], v[224:227], v[184:187], v[104:107]
	v_mfma_f32_16x16x32_bf16 v[92:95], v[216:219], v[192:195], v[92:95]
	v_mfma_f32_16x16x32_bf16 v[88:91], v[224:227], v[192:195], v[88:91]
	v_mfma_f32_16x16x32_bf16 v[76:79], v[216:219], v[200:203], v[76:79]
	v_mfma_f32_16x16x32_bf16 v[72:75], v[224:227], v[200:203], v[72:75]
	v_mfma_f32_16x16x32_bf16 v[68:71], v[216:219], v[208:211], v[68:71]
	v_mfma_f32_16x16x32_bf16 v[64:67], v[224:227], v[208:211], v[64:67]
	s_barrier
	s_setprio 0
	s_add_i32 s17, s17, s85
	v_lshl_add_u64 v[152:153], s[44:45], 0, v[154:155]
	s_mov_b32 m0, s17
	v_lshl_add_u64 v[228:229], s[44:45], 0, v[132:133]
	global_load_lds_dwordx4 v[152:153], off
	s_add_i32 m0, s17, 0x2000
	s_nop 0
	global_load_lds_dwordx4 v[228:229], off
	s_mov_b32 m0, s88
	v_lshl_add_u64 v[230:231], s[34:35], 0, v[128:129]
	ds_read_b128 v[168:171], v143 offset:16384
	ds_read_b128 v[184:187], v143 offset:17408
	ds_read_b128 v[188:191], v143 offset:18432
	ds_read_b128 v[192:195], v143 offset:19456
	ds_read_b128 v[196:199], v143 offset:20480
	ds_read_b128 v[200:203], v143 offset:21504
	ds_read_b128 v[204:207], v143 offset:22528
	ds_read_b128 v[208:211], v143 offset:23552
	global_load_lds_dwordx4 v[230:231], off
	v_lshl_add_u64 v[232:233], s[34:35], 0, v[130:131]
	s_mov_b32 m0, s89
	s_nop 0
	global_load_lds_dwordx4 v[232:233], off
	s_add_u32 s44, s44, s6
	s_addc_u32 s45, s45, 0
	s_add_i32 s1, s1, s85
	v_lshl_add_u64 v[234:235], s[44:45], 0, v[154:155]
	s_mov_b32 m0, s1
	v_lshl_add_u64 v[236:237], s[44:45], 0, v[132:133]
	global_load_lds_dwordx4 v[234:235], off
	s_add_i32 m0, s1, 0x2000
	s_nop 0
	global_load_lds_dwordx4 v[236:237], off
	s_waitcnt vmcnt(24)
	s_waitcnt lgkmcnt(0)
	s_setprio 1
	s_barrier
; #define PG8_STAGE(bufoff, gbase, voff) do { _Pragma("unroll") for (int _i = 0; _i < 2; ++_i) \
;         __builtin_amdgcn_global_load_lds((const unsigned*)((const char*)(gbase) + (voff)[_i]), (LAS unsigned*)(lds + (bufoff) + ldsw + _i * 8192), 16, 0, 0); } while (0)
; #define PG8_LDA(dst, b, h) do { _Pragma("unroll") for (int m = 0; m < 4; ++m) _Pragma("unroll") for (int k = 0; k < 2; ++k) dst[m][k] = *(const LAS bf16x8*)(lds + PG8_SA(b, h) + aoff + m * 2048 + k * 1024); } while (0)
; #define PG8_LDB(dst, b, h) do { _Pragma("unroll") for (int n = 0; n < 2; ++n) _Pragma("unroll") for (int k = 0; k < 2; ++k) dst[n][k] = *(const LAS bf16x8*)(lds + PG8_SB(b, h) + boff + n * 2048 + k * 1024); } while (0)
; #define PG8_MMA(ai, bj, At, Bt) do { __builtin_amdgcn_s_setprio(1); _Pragma("unroll") for (int m = 0; m < 4; ++m) _Pragma("unroll") for (int n = 0; n < 2; ++n) _Pragma("unroll") for (int k = 0; k < 2; ++k) \
;         acc[ai][bj][m][n] = __builtin_amdgcn_mfma_f32_16x16x32_bf16(Bt[n][k], At[m][k], acc[ai][bj][m][n], 0, 0, 0); __builtin_amdgcn_s_setprio(0); } while (0)
; #define PG8_WAIT_V(n) asm volatile("s_waitcnt vmcnt(" #n ")" ::: "memory")
; #define PG8_WAIT_L(n) asm volatile("s_waitcnt lgkmcnt(" #n ")" ::: "memory")
; #define PG8_BAR __builtin_amdgcn_s_barrier()
; #define PG8_SCHED __builtin_amdgcn_sched_barrier(0)
; template <class Epi, class Sched>
; __device__ __forceinline__ void gemm_phase(LAS unsigned char* lds, const Gemm g, const Sched& S, const Epi& E, int tid) {
;     ...
;             PG8_BAR; PG8_WAIT_L(0); PG8_MMA(1, 0, At, B0); PG8_BAR; PG8_SCHED;
;             PG8_STAGE(PG8_SB(0, 1), b2 + hstep, voffB);
;             PG8_WAIT_V(6); PG8_BAR; PG8_MMA(1, 1, At, B1); PG8_BAR;
;             PG8_LDB(B0, 1, 0); PG8_SCHED; PG8_LDA(At, 1, 0); PG8_STAGE(PG8_SA(0, 1), a2 + hstep, voffA);
;             PG8_WAIT_L(8); PG8_BAR; PG8_WAIT_L(0); PG8_MMA(0, 0, At, B0); PG8_BAR; PG8_SCHED;
;             PG8_LDB(B1, 1, 1); PG8_STAGE(PG8_SB(1, 0), b3, voffB);
;             PG8_BAR; PG8_WAIT_L(0); PG8_MMA(0, 1, At, B1); PG8_BAR;
	v_mfma_f32_16x16x32_bf16 v[60:63], v[144:147], v[168:171], 0
	v_mfma_f32_16x16x32_bf16 v[56:59], v[160:163], v[168:171], 0
	v_mfma_f32_16x16x32_bf16 v[52:55], v[144:147], v[188:191], 0
	s_add_i32 s1, 0, 0x18000
	v_mfma_f32_16x16x32_bf16 v[48:51], v[160:163], v[188:191], 0
	v_add_u32_e32 v241, s1, v141
	v_mfma_f32_16x16x32_bf16 v[36:39], v[144:147], v[196:199], 0
	v_mfma_f32_16x16x32_bf16 v[32:35], v[160:163], v[196:199], 0
	v_mfma_f32_16x16x32_bf16 v[20:23], v[144:147], v[204:207], 0
	v_mfma_f32_16x16x32_bf16 v[16:19], v[160:163], v[204:207], 0
	v_mfma_f32_16x16x32_bf16 v[60:63], v[148:151], v[184:187], v[60:63]
	v_mfma_f32_16x16x32_bf16 v[56:59], v[164:167], v[184:187], v[56:59]
	v_mfma_f32_16x16x32_bf16 v[52:55], v[148:151], v[192:195], v[52:55]
	v_mfma_f32_16x16x32_bf16 v[48:51], v[164:167], v[192:195], v[48:51]
	v_mfma_f32_16x16x32_bf16 v[36:39], v[148:151], v[200:203], v[36:39]
	v_mfma_f32_16x16x32_bf16 v[32:35], v[164:167], v[200:203], v[32:35]
	v_mfma_f32_16x16x32_bf16 v[20:23], v[148:151], v[208:211], v[20:23]
	v_mfma_f32_16x16x32_bf16 v[16:19], v[164:167], v[208:211], v[16:19]
	v_mfma_f32_16x16x32_bf16 v[44:47], v[212:215], v[168:171], 0
	v_mfma_f32_16x16x32_bf16 v[40:43], v[220:223], v[168:171], 0
	v_mfma_f32_16x16x32_bf16 v[28:31], v[212:215], v[188:191], 0
	v_mfma_f32_16x16x32_bf16 v[24:27], v[220:223], v[188:191], 0
	v_mfma_f32_16x16x32_bf16 v[12:15], v[212:215], v[196:199], 0
	v_mfma_f32_16x16x32_bf16 v[8:11], v[220:223], v[196:199], 0
	v_mfma_f32_16x16x32_bf16 v[4:7], v[212:215], v[204:207], 0
	v_mfma_f32_16x16x32_bf16 v[0:3], v[220:223], v[204:207], 0
	v_mfma_f32_16x16x32_bf16 v[44:47], v[216:219], v[184:187], v[44:47]
	v_mfma_f32_16x16x32_bf16 v[40:43], v[224:227], v[184:187], v[40:43]
	v_mfma_f32_16x16x32_bf16 v[28:31], v[216:219], v[192:195], v[28:31]
	v_mfma_f32_16x16x32_bf16 v[24:27], v[224:227], v[192:195], v[24:27]
	v_mfma_f32_16x16x32_bf16 v[12:15], v[216:219], v[200:203], v[12:15]
	v_mfma_f32_16x16x32_bf16 v[8:11], v[224:227], v[200:203], v[8:11]
	v_mfma_f32_16x16x32_bf16 v[4:7], v[216:219], v[208:211], v[4:7]
	v_mfma_f32_16x16x32_bf16 v[0:3], v[224:227], v[208:211], v[0:3]
	s_barrier
	s_setprio 0
	ds_read_b128 v[144:147], v241
	ds_read_b128 v[148:151], v241 offset:1024
	ds_read_b128 v[160:163], v241 offset:2048
	ds_read_b128 v[164:167], v241 offset:3072
	s_add_u32 s34, s34, s6
	s_addc_u32 s35, s35, 0
	s_mov_b32 m0, s90
	v_lshl_add_u64 v[212:213], s[34:35], 0, v[128:129]
	ds_read_b128 v[168:171], v143 offset:32768
	ds_read_b128 v[184:187], v143 offset:33792
	ds_read_b128 v[188:191], v143 offset:34816
	ds_read_b128 v[192:195], v143 offset:35840
	ds_read_b128 v[196:199], v143 offset:36864
	ds_read_b128 v[200:203], v143 offset:37888
	ds_read_b128 v[204:207], v143 offset:38912
	ds_read_b128 v[208:211], v143 offset:39936
	global_load_lds_dwordx4 v[212:213], off
	v_lshl_add_u64 v[212:213], s[34:35], 0, v[130:131]
	s_mov_b32 m0, s91
	s_nop 0
	global_load_lds_dwordx4 v[212:213], off
	s_add_i32 s17, 0, 0x1c000
	v_add_u32_e32 v183, s17, v141
	ds_read_b128 v[212:215], v183
	ds_read_b128 v[216:219], v183 offset:1024
	ds_read_b128 v[220:223], v183 offset:2048
	ds_read_b128 v[224:227], v183 offset:3072
	s_waitcnt vmcnt(8)
	s_waitcnt lgkmcnt(0)
	s_setprio 1
	s_barrier
	v_mfma_f32_16x16x32_bf16 v[124:127], v[144:147], v[168:171], v[124:127]
	v_mfma_f32_16x16x32_bf16 v[120:123], v[160:163], v[168:171], v[120:123]
	v_mfma_f32_16x16x32_bf16 v[116:119], v[144:147], v[188:191], v[116:119]
	v_mfma_f32_16x16x32_bf16 v[112:115], v[160:163], v[188:191], v[112:115]
	v_mfma_f32_16x16x32_bf16 v[100:103], v[144:147], v[196:199], v[100:103]
	v_mfma_f32_16x16x32_bf16 v[96:99], v[160:163], v[196:199], v[96:99]
	v_mfma_f32_16x16x32_bf16 v[84:87], v[144:147], v[204:207], v[84:87]
	v_mfma_f32_16x16x32_bf16 v[80:83], v[160:163], v[204:207], v[80:83]
	v_mfma_f32_16x16x32_bf16 v[124:127], v[148:151], v[184:187], v[124:127]
	v_mfma_f32_16x16x32_bf16 v[120:123], v[164:167], v[184:187], v[120:123]
	v_mfma_f32_16x16x32_bf16 v[116:119], v[148:151], v[192:195], v[116:119]
	v_mfma_f32_16x16x32_bf16 v[112:115], v[164:167], v[192:195], v[112:115]
	v_mfma_f32_16x16x32_bf16 v[100:103], v[148:151], v[200:203], v[100:103]
	v_mfma_f32_16x16x32_bf16 v[96:99], v[164:167], v[200:203], v[96:99]
	v_mfma_f32_16x16x32_bf16 v[84:87], v[148:151], v[208:211], v[84:87]
	v_mfma_f32_16x16x32_bf16 v[80:83], v[164:167], v[208:211], v[80:83]
	v_mfma_f32_16x16x32_bf16 v[108:111], v[212:215], v[168:171], v[108:111]
	v_mfma_f32_16x16x32_bf16 v[104:107], v[220:223], v[168:171], v[104:107]
	v_mfma_f32_16x16x32_bf16 v[92:95], v[212:215], v[188:191], v[92:95]
	v_mfma_f32_16x16x32_bf16 v[88:91], v[220:223], v[188:191], v[88:91]
	v_mfma_f32_16x16x32_bf16 v[76:79], v[212:215], v[196:199], v[76:79]
	v_mfma_f32_16x16x32_bf16 v[72:75], v[220:223], v[196:199], v[72:75]
	v_mfma_f32_16x16x32_bf16 v[68:71], v[212:215], v[204:207], v[68:71]
	v_mfma_f32_16x16x32_bf16 v[64:67], v[220:223], v[204:207], v[64:67]
	v_mfma_f32_16x16x32_bf16 v[108:111], v[216:219], v[184:187], v[108:111]
	v_mfma_f32_16x16x32_bf16 v[104:107], v[224:227], v[184:187], v[104:107]
	v_mfma_f32_16x16x32_bf16 v[92:95], v[216:219], v[192:195], v[92:95]
	v_mfma_f32_16x16x32_bf16 v[88:91], v[224:227], v[192:195], v[88:91]
	v_mfma_f32_16x16x32_bf16 v[76:79], v[216:219], v[200:203], v[76:79]
	v_mfma_f32_16x16x32_bf16 v[72:75], v[224:227], v[200:203], v[72:75]
	v_mfma_f32_16x16x32_bf16 v[68:71], v[216:219], v[208:211], v[68:71]
	v_mfma_f32_16x16x32_bf16 v[64:67], v[224:227], v[208:211], v[64:67]
	s_barrier
; #define PG8_STAGE(bufoff, gbase, voff) do { _Pragma("unroll") for (int _i = 0; _i < 2; ++_i) \
;         __builtin_amdgcn_global_load_lds((const unsigned*)((const char*)(gbase) + (voff)[_i]), (LAS unsigned*)(lds + (bufoff) + ldsw + _i * 8192), 16, 0, 0); } while (0)
; #define PG8_LDA(dst, b, h) do { _Pragma("unroll") for (int m = 0; m < 4; ++m) _Pragma("unroll") for (int k = 0; k < 2; ++k) dst[m][k] = *(const LAS bf16x8*)(lds + PG8_SA(b, h) + aoff + m * 2048 + k * 1024); } while (0)
; #define PG8_LDB(dst, b, h) do { _Pragma("unroll") for (int n = 0; n < 2; ++n) _Pragma("unroll") for (int k = 0; k < 2; ++k) dst[n][k] = *(const LAS bf16x8*)(lds + PG8_SB(b, h) + boff + n * 2048 + k * 1024); } while (0)
; #define PG8_MMA(ai, bj, At, Bt) do { __builtin_amdgcn_s_setprio(1); _Pragma("unroll") for (int m = 0; m < 4; ++m) _Pragma("unroll") for (int n = 0; n < 2; ++n) _Pragma("unroll") for (int k = 0; k < 2; ++k) \
;         acc[ai][bj][m][n] = __builtin_amdgcn_mfma_f32_16x16x32_bf16(Bt[n][k], At[m][k], acc[ai][bj][m][n], 0, 0, 0); __builtin_amdgcn_s_setprio(0); } while (0)
; #define PG8_WAIT_V(n) asm volatile("s_waitcnt vmcnt(" #n ")" ::: "memory")
; #define PG8_WAIT_L(n) asm volatile("s_waitcnt lgkmcnt(" #n ")" ::: "memory")
; #define PG8_BAR __builtin_amdgcn_s_barrier()
; #define PG8_SCHED __builtin_amdgcn_sched_barrier(0)
; template <class Epi, class Sched>
; __device__ __forceinline__ void gemm_phase(LAS unsigned char* lds, const Gemm g, const Sched& S, const Epi& E, int tid) {
;     ...
;             PG8_LDB(B0, 0, 0); PG8_SCHED; PG8_LDA(At, 0, 0); PG8_STAGE(PG8_SA(1, 1), a1 + hstep, voffA);
;             PG8_WAIT_L(8); PG8_BAR; PG8_WAIT_L(0); PG8_MMA(0, 0, At, B0); PG8_BAR; PG8_SCHED;
;             PG8_LDB(B1, 0, 1); PG8_STAGE(PG8_SB(0, 0), b2, voffB);
;     ...
;             PG8_LDA(At, 1, 1); PG8_STAGE(PG8_SA(1, 0), a3, voffA);
;             PG8_BAR; PG8_WAIT_L(0); PG8_MMA(1, 0, At, B0); PG8_BAR; PG8_SCHED;
;             PG8_STAGE(PG8_SB(1, 1), b3 + hstep, voffB);
;             PG8_WAIT_V(6); PG8_BAR; PG8_MMA(1, 1, At, B1); PG8_BAR;
	s_setprio 0
	s_add_i32 s1, s1, s85
	v_lshl_add_u64 v[152:153], v[152:153], 0, s[8:9]
	s_mov_b32 m0, s1
	global_load_lds_dwordx4 v[152:153], off
	v_lshl_add_u64 v[152:153], v[228:229], 0, s[8:9]
	s_add_i32 m0, s1, 0x2000
	s_nop 0
	global_load_lds_dwordx4 v[152:153], off
	s_mov_b32 m0, s92
	v_lshl_add_u64 v[152:153], v[230:231], 0, s[8:9]
	ds_read_b128 v[168:171], v143 offset:49152
	ds_read_b128 v[184:187], v143 offset:50176
	ds_read_b128 v[188:191], v143 offset:51200
	ds_read_b128 v[192:195], v143 offset:52224
	ds_read_b128 v[196:199], v143 offset:53248
	ds_read_b128 v[200:203], v143 offset:54272
	ds_read_b128 v[204:207], v143 offset:55296
	ds_read_b128 v[208:211], v143 offset:56320
	global_load_lds_dwordx4 v[152:153], off
	v_lshl_add_u64 v[152:153], v[232:233], 0, s[8:9]
	s_mov_b32 m0, s93
	s_nop 0
	global_load_lds_dwordx4 v[152:153], off
	s_add_i32 s1, s17, s85
	v_lshl_add_u64 v[238:239], v[234:235], 0, s[8:9]
	s_mov_b32 m0, s1
	s_nop 0
	global_load_lds_dwordx4 v[238:239], off
	v_lshl_add_u64 v[238:239], v[236:237], 0, s[8:9]
	s_add_i32 m0, s1, 0x2000
	s_nop 0
	global_load_lds_dwordx4 v[238:239], off
	s_waitcnt vmcnt(6)
	s_waitcnt lgkmcnt(0)
	s_setprio 1
	s_barrier
	v_mfma_f32_16x16x32_bf16 v[60:63], v[144:147], v[168:171], v[60:63]
	v_mfma_f32_16x16x32_bf16 v[56:59], v[160:163], v[168:171], v[56:59]
	v_mfma_f32_16x16x32_bf16 v[52:55], v[144:147], v[188:191], v[52:55]
	s_add_u32 vcc_lo, vcc_lo, 0x100
	v_mfma_f32_16x16x32_bf16 v[48:51], v[160:163], v[188:191], v[48:51]
	s_addc_u32 vcc_hi, vcc_hi, 0
	v_mfma_f32_16x16x32_bf16 v[36:39], v[144:147], v[196:199], v[36:39]
	s_add_u32 s96, s96, 0x100
	v_mfma_f32_16x16x32_bf16 v[32:35], v[160:163], v[196:199], v[32:35]
	s_addc_u32 s65, s65, 0
	v_mfma_f32_16x16x32_bf16 v[20:23], v[144:147], v[204:207], v[20:23]
	s_cmp_ge_u32 s0, s94
	v_mfma_f32_16x16x32_bf16 v[16:19], v[160:163], v[204:207], v[16:19]
	s_mov_b32 s34, s0
	v_mfma_f32_16x16x32_bf16 v[60:63], v[148:151], v[184:187], v[60:63]
	v_mfma_f32_16x16x32_bf16 v[56:59], v[164:167], v[184:187], v[56:59]
	v_mfma_f32_16x16x32_bf16 v[52:55], v[148:151], v[192:195], v[52:55]
	v_mfma_f32_16x16x32_bf16 v[48:51], v[164:167], v[192:195], v[48:51]
	v_mfma_f32_16x16x32_bf16 v[36:39], v[148:151], v[200:203], v[36:39]
	v_mfma_f32_16x16x32_bf16 v[32:35], v[164:167], v[200:203], v[32:35]
	v_mfma_f32_16x16x32_bf16 v[20:23], v[148:151], v[208:211], v[20:23]
	v_mfma_f32_16x16x32_bf16 v[16:19], v[164:167], v[208:211], v[16:19]
	v_mfma_f32_16x16x32_bf16 v[44:47], v[212:215], v[168:171], v[44:47]
	v_mfma_f32_16x16x32_bf16 v[40:43], v[220:223], v[168:171], v[40:43]
	v_mfma_f32_16x16x32_bf16 v[28:31], v[212:215], v[188:191], v[28:31]
	v_mfma_f32_16x16x32_bf16 v[24:27], v[220:223], v[188:191], v[24:27]
	v_mfma_f32_16x16x32_bf16 v[12:15], v[212:215], v[196:199], v[12:15]
	v_mfma_f32_16x16x32_bf16 v[8:11], v[220:223], v[196:199], v[8:11]
	v_mfma_f32_16x16x32_bf16 v[4:7], v[212:215], v[204:207], v[4:7]
	v_mfma_f32_16x16x32_bf16 v[0:3], v[220:223], v[204:207], v[0:3]
	v_mfma_f32_16x16x32_bf16 v[44:47], v[216:219], v[184:187], v[44:47]
	v_mfma_f32_16x16x32_bf16 v[40:43], v[224:227], v[184:187], v[40:43]
	v_mfma_f32_16x16x32_bf16 v[28:31], v[216:219], v[192:195], v[28:31]
	v_mfma_f32_16x16x32_bf16 v[24:27], v[224:227], v[192:195], v[24:27]
	v_mfma_f32_16x16x32_bf16 v[12:15], v[216:219], v[200:203], v[12:15]
	v_mfma_f32_16x16x32_bf16 v[8:11], v[224:227], v[200:203], v[8:11]
	v_mfma_f32_16x16x32_bf16 v[4:7], v[216:219], v[208:211], v[4:7]
	v_mfma_f32_16x16x32_bf16 v[0:3], v[224:227], v[208:211], v[0:3]
	s_barrier
	s_setprio 0
	s_cbranch_scc1 .Lpeel_exit_plain
.LBB0_100:
	s_add_i32 s0, s34, 2
	s_add_u32 s1, vcc_lo, 0x80
	s_addc_u32 s35, vcc_hi, 0
	s_add_i32 s17, 0, 0x10000
	v_add_u32_e32 v152, s17, v141
	ds_read_b128 v[144:147], v152
	ds_read_b128 v[148:151], v152 offset:1024
	ds_read_b128 v[160:163], v152 offset:2048
	ds_read_b128 v[164:167], v152 offset:3072
	s_cmp_eq_u32 s95, s34
	s_cselect_b32 s34, s38, s1
	s_cselect_b32 s35, s39, s35
	s_cselect_b32 s45, s41, s65
	s_cselect_b32 s44, s40, s96
	v_lshl_add_u64 v[152:153], vcc, 0, v[134:135]
	s_add_i32 m0, s88, 0xc000
	ds_read_b128 v[168:171], v143
	ds_read_b128 v[184:187], v143 offset:1024
	ds_read_b128 v[188:191], v143 offset:2048
	ds_read_b128 v[192:195], v143 offset:3072
	ds_read_b128 v[196:199], v143 offset:4096
	ds_read_b128 v[200:203], v143 offset:5120
	ds_read_b128 v[204:207], v143 offset:6144
	ds_read_b128 v[208:211], v143 offset:7168
	global_load_lds_dwordx4 v[152:153], off
	v_lshl_add_u64 v[152:153], vcc, 0, v[136:137]
	s_add_i32 m0, s88, 0xe000
	s_nop 0
	global_load_lds_dwordx4 v[152:153], off
	s_add_i32 s1, 0, 0x14000
	v_add_u32_e32 v152, s1, v141
	ds_read_b128 v[212:215], v152
	ds_read_b128 v[216:219], v152 offset:1024
	ds_read_b128 v[220:223], v152 offset:2048
	ds_read_b128 v[224:227], v152 offset:3072
	s_waitcnt lgkmcnt(0)
	s_setprio 1
	s_barrier
; #define PG8_STAGE(bufoff, gbase, voff) do { _Pragma("unroll") for (int _i = 0; _i < 2; ++_i) \
;         __builtin_amdgcn_global_load_lds((const unsigned*)((const char*)(gbase) + (voff)[_i]), (LAS unsigned*)(lds + (bufoff) + ldsw + _i * 8192), 16, 0, 0); } while (0)
; #define PG8_LDA(dst, b, h) do { _Pragma("unroll") for (int m = 0; m < 4; ++m) _Pragma("unroll") for (int k = 0; k < 2; ++k) dst[m][k] = *(const LAS bf16x8*)(lds + PG8_SA(b, h) + aoff + m * 2048 + k * 1024); } while (0)
; #define PG8_LDB(dst, b, h) do { _Pragma("unroll") for (int n = 0; n < 2; ++n) _Pragma("unroll") for (int k = 0; k < 2; ++k) dst[n][k] = *(const LAS bf16x8*)(lds + PG8_SB(b, h) + boff + n * 2048 + k * 1024); } while (0)
; #define PG8_MMA(ai, bj, At, Bt) do { __builtin_amdgcn_s_setprio(1); _Pragma("unroll") for (int m = 0; m < 4; ++m) _Pragma("unroll") for (int n = 0; n < 2; ++n) _Pragma("unroll") for (int k = 0; k < 2; ++k) \
;         acc[ai][bj][m][n] = __builtin_amdgcn_mfma_f32_16x16x32_bf16(Bt[n][k], At[m][k], acc[ai][bj][m][n], 0, 0, 0); __builtin_amdgcn_s_setprio(0); } while (0)
; #define PG8_WAIT_V(n) asm volatile("s_waitcnt vmcnt(" #n ")" ::: "memory")
; #define PG8_WAIT_L(n) asm volatile("s_waitcnt lgkmcnt(" #n ")" ::: "memory")
; #define PG8_BAR __builtin_amdgcn_s_barrier()
; #define PG8_SCHED __builtin_amdgcn_sched_barrier(0)
; template <class Epi, class Sched>
; __device__ __forceinline__ void gemm_phase(LAS unsigned char* lds, const Gemm g, const Sched& S, const Epi& E, int tid) {
;     ...
;             PG8_LDB(B0, 0, 0); PG8_SCHED; PG8_LDA(At, 0, 0); PG8_STAGE(PG8_SA(1, 1), a1 + hstep, voffA);
;             PG8_WAIT_L(8); PG8_BAR; PG8_WAIT_L(0); PG8_MMA(0, 0, At, B0); PG8_BAR; PG8_SCHED;
;             PG8_LDB(B1, 0, 1); PG8_STAGE(PG8_SB(0, 0), b2, voffB);
;             PG8_BAR; PG8_WAIT_L(0); PG8_MMA(0, 1, At, B1); PG8_BAR;
;             PG8_LDA(At, 0, 1); PG8_STAGE(PG8_SA(0, 0), a2, voffA);
;             PG8_BAR; PG8_WAIT_L(0); PG8_MMA(1, 0, At, B0); PG8_BAR; PG8_SCHED;
;             PG8_STAGE(PG8_SB(0, 1), b2 + hstep, voffB);
;             PG8_WAIT_V(6); PG8_BAR; PG8_MMA(1, 1, At, B1); PG8_BAR;
	v_mfma_f32_16x16x32_bf16 v[124:127], v[144:147], v[168:171], v[124:127]
	v_mfma_f32_16x16x32_bf16 v[120:123], v[160:163], v[168:171], v[120:123]
	v_mfma_f32_16x16x32_bf16 v[116:119], v[144:147], v[188:191], v[116:119]
	v_mfma_f32_16x16x32_bf16 v[112:115], v[160:163], v[188:191], v[112:115]
	v_mfma_f32_16x16x32_bf16 v[100:103], v[144:147], v[196:199], v[100:103]
	v_mfma_f32_16x16x32_bf16 v[96:99], v[160:163], v[196:199], v[96:99]
	v_mfma_f32_16x16x32_bf16 v[84:87], v[144:147], v[204:207], v[84:87]
	v_mfma_f32_16x16x32_bf16 v[80:83], v[160:163], v[204:207], v[80:83]
	v_mfma_f32_16x16x32_bf16 v[124:127], v[148:151], v[184:187], v[124:127]
	v_mfma_f32_16x16x32_bf16 v[120:123], v[164:167], v[184:187], v[120:123]
	v_mfma_f32_16x16x32_bf16 v[116:119], v[148:151], v[192:195], v[116:119]
	v_mfma_f32_16x16x32_bf16 v[112:115], v[164:167], v[192:195], v[112:115]
	v_mfma_f32_16x16x32_bf16 v[100:103], v[148:151], v[200:203], v[100:103]
	v_mfma_f32_16x16x32_bf16 v[96:99], v[164:167], v[200:203], v[96:99]
	v_mfma_f32_16x16x32_bf16 v[84:87], v[148:151], v[208:211], v[84:87]
	v_mfma_f32_16x16x32_bf16 v[80:83], v[164:167], v[208:211], v[80:83]
	v_mfma_f32_16x16x32_bf16 v[108:111], v[212:215], v[168:171], v[108:111]
	v_mfma_f32_16x16x32_bf16 v[104:107], v[220:223], v[168:171], v[104:107]
	v_mfma_f32_16x16x32_bf16 v[92:95], v[212:215], v[188:191], v[92:95]
	v_mfma_f32_16x16x32_bf16 v[88:91], v[220:223], v[188:191], v[88:91]
	v_mfma_f32_16x16x32_bf16 v[76:79], v[212:215], v[196:199], v[76:79]
	v_mfma_f32_16x16x32_bf16 v[72:75], v[220:223], v[196:199], v[72:75]
	v_mfma_f32_16x16x32_bf16 v[68:71], v[212:215], v[204:207], v[68:71]
	v_mfma_f32_16x16x32_bf16 v[64:67], v[220:223], v[204:207], v[64:67]
	v_mfma_f32_16x16x32_bf16 v[108:111], v[216:219], v[184:187], v[108:111]
	v_mfma_f32_16x16x32_bf16 v[104:107], v[224:227], v[184:187], v[104:107]
	v_mfma_f32_16x16x32_bf16 v[92:95], v[216:219], v[192:195], v[92:95]
	v_mfma_f32_16x16x32_bf16 v[88:91], v[224:227], v[192:195], v[88:91]
	v_mfma_f32_16x16x32_bf16 v[76:79], v[216:219], v[200:203], v[76:79]
	v_mfma_f32_16x16x32_bf16 v[72:75], v[224:227], v[200:203], v[72:75]
	v_mfma_f32_16x16x32_bf16 v[68:71], v[216:219], v[208:211], v[68:71]
	v_mfma_f32_16x16x32_bf16 v[64:67], v[224:227], v[208:211], v[64:67]
	s_barrier
	s_setprio 0
	s_add_i32 s17, s17, s85
	v_lshl_add_u64 v[152:153], s[44:45], 0, v[154:155]
	s_mov_b32 m0, s17
	v_lshl_add_u64 v[228:229], s[44:45], 0, v[132:133]
	global_load_lds_dwordx4 v[152:153], off
	s_add_i32 m0, s17, 0x2000
	s_nop 0
	global_load_lds_dwordx4 v[228:229], off
	s_mov_b32 m0, s88
	v_lshl_add_u64 v[230:231], s[34:35], 0, v[128:129]
	ds_read_b128 v[168:171], v143 offset:16384
	ds_read_b128 v[184:187], v143 offset:17408
	ds_read_b128 v[188:191], v143 offset:18432
	ds_read_b128 v[192:195], v143 offset:19456
	ds_read_b128 v[196:199], v143 offset:20480
	ds_read_b128 v[200:203], v143 offset:21504
	ds_read_b128 v[204:207], v143 offset:22528
	ds_read_b128 v[208:211], v143 offset:23552
	global_load_lds_dwordx4 v[230:231], off
	v_lshl_add_u64 v[232:233], s[34:35], 0, v[130:131]
	s_mov_b32 m0, s89
	s_nop 0
	global_load_lds_dwordx4 v[232:233], off
	s_add_u32 s44, s44, s6
	s_addc_u32 s45, s45, 0
	s_add_i32 s1, s1, s85
	v_lshl_add_u64 v[234:235], s[44:45], 0, v[154:155]
	s_mov_b32 m0, s1
	v_lshl_add_u64 v[236:237], s[44:45], 0, v[132:133]
	global_load_lds_dwordx4 v[234:235], off
	s_add_i32 m0, s1, 0x2000
	s_nop 0
	global_load_lds_dwordx4 v[236:237], off
	s_waitcnt vmcnt(6)
	s_waitcnt lgkmcnt(0)
	s_setprio 1
	s_barrier
	v_mfma_f32_16x16x32_bf16 v[60:63], v[144:147], v[168:171], v[60:63]
	v_mfma_f32_16x16x32_bf16 v[56:59], v[160:163], v[168:171], v[56:59]
	v_mfma_f32_16x16x32_bf16 v[52:55], v[144:147], v[188:191], v[52:55]
	s_add_i32 s1, 0, 0x18000
	v_mfma_f32_16x16x32_bf16 v[48:51], v[160:163], v[188:191], v[48:51]
	v_add_u32_e32 v241, s1, v141
	v_mfma_f32_16x16x32_bf16 v[36:39], v[144:147], v[196:199], v[36:39]
	v_mfma_f32_16x16x32_bf16 v[32:35], v[160:163], v[196:199], v[32:35]
	v_mfma_f32_16x16x32_bf16 v[20:23], v[144:147], v[204:207], v[20:23]
	v_mfma_f32_16x16x32_bf16 v[16:19], v[160:163], v[204:207], v[16:19]
	v_mfma_f32_16x16x32_bf16 v[60:63], v[148:151], v[184:187], v[60:63]
	v_mfma_f32_16x16x32_bf16 v[56:59], v[164:167], v[184:187], v[56:59]
	v_mfma_f32_16x16x32_bf16 v[52:55], v[148:151], v[192:195], v[52:55]
	v_mfma_f32_16x16x32_bf16 v[48:51], v[164:167], v[192:195], v[48:51]
	v_mfma_f32_16x16x32_bf16 v[36:39], v[148:151], v[200:203], v[36:39]
	v_mfma_f32_16x16x32_bf16 v[32:35], v[164:167], v[200:203], v[32:35]
	v_mfma_f32_16x16x32_bf16 v[20:23], v[148:151], v[208:211], v[20:23]
	v_mfma_f32_16x16x32_bf16 v[16:19], v[164:167], v[208:211], v[16:19]
	v_mfma_f32_16x16x32_bf16 v[44:47], v[212:215], v[168:171], v[44:47]
	v_mfma_f32_16x16x32_bf16 v[40:43], v[220:223], v[168:171], v[40:43]
	v_mfma_f32_16x16x32_bf16 v[28:31], v[212:215], v[188:191], v[28:31]
	v_mfma_f32_16x16x32_bf16 v[24:27], v[220:223], v[188:191], v[24:27]
	v_mfma_f32_16x16x32_bf16 v[12:15], v[212:215], v[196:199], v[12:15]
	v_mfma_f32_16x16x32_bf16 v[8:11], v[220:223], v[196:199], v[8:11]
	v_mfma_f32_16x16x32_bf16 v[4:7], v[212:215], v[204:207], v[4:7]
	v_mfma_f32_16x16x32_bf16 v[0:3], v[220:223], v[204:207], v[0:3]
	v_mfma_f32_16x16x32_bf16 v[44:47], v[216:219], v[184:187], v[44:47]
	v_mfma_f32_16x16x32_bf16 v[40:43], v[224:227], v[184:187], v[40:43]
	v_mfma_f32_16x16x32_bf16 v[28:31], v[216:219], v[192:195], v[28:31]
	v_mfma_f32_16x16x32_bf16 v[24:27], v[224:227], v[192:195], v[24:27]
	v_mfma_f32_16x16x32_bf16 v[12:15], v[216:219], v[200:203], v[12:15]
	v_mfma_f32_16x16x32_bf16 v[8:11], v[224:227], v[200:203], v[8:11]
	v_mfma_f32_16x16x32_bf16 v[4:7], v[216:219], v[208:211], v[4:7]
	v_mfma_f32_16x16x32_bf16 v[0:3], v[224:227], v[208:211], v[0:3]
	s_barrier
; #define PG8_STAGE(bufoff, gbase, voff) do { _Pragma("unroll") for (int _i = 0; _i < 2; ++_i) \
;         __builtin_amdgcn_global_load_lds((const unsigned*)((const char*)(gbase) + (voff)[_i]), (LAS unsigned*)(lds + (bufoff) + ldsw + _i * 8192), 16, 0, 0); } while (0)
; #define PG8_LDA(dst, b, h) do { _Pragma("unroll") for (int m = 0; m < 4; ++m) _Pragma("unroll") for (int k = 0; k < 2; ++k) dst[m][k] = *(const LAS bf16x8*)(lds + PG8_SA(b, h) + aoff + m * 2048 + k * 1024); } while (0)
; #define PG8_LDB(dst, b, h) do { _Pragma("unroll") for (int n = 0; n < 2; ++n) _Pragma("unroll") for (int k = 0; k < 2; ++k) dst[n][k] = *(const LAS bf16x8*)(lds + PG8_SB(b, h) + boff + n * 2048 + k * 1024); } while (0)
; #define PG8_MMA(ai, bj, At, Bt) do { __builtin_amdgcn_s_setprio(1); _Pragma("unroll") for (int m = 0; m < 4; ++m) _Pragma("unroll") for (int n = 0; n < 2; ++n) _Pragma("unroll") for (int k = 0; k < 2; ++k) \
;         acc[ai][bj][m][n] = __builtin_amdgcn_mfma_f32_16x16x32_bf16(Bt[n][k], At[m][k], acc[ai][bj][m][n], 0, 0, 0); __builtin_amdgcn_s_setprio(0); } while (0)
; #define PG8_WAIT_V(n) asm volatile("s_waitcnt vmcnt(" #n ")" ::: "memory")
; #define PG8_WAIT_L(n) asm volatile("s_waitcnt lgkmcnt(" #n ")" ::: "memory")
; #define PG8_BAR __builtin_amdgcn_s_barrier()
; #define PG8_SCHED __builtin_amdgcn_sched_barrier(0)
; template <class Epi, class Sched>
; __device__ __forceinline__ void gemm_phase(LAS unsigned char* lds, const Gemm g, const Sched& S, const Epi& E, int tid) {
;     ...
;             PG8_LDB(B0, 1, 0); PG8_SCHED; PG8_LDA(At, 1, 0); PG8_STAGE(PG8_SA(0, 1), a2 + hstep, voffA);
;             PG8_WAIT_L(8); PG8_BAR; PG8_WAIT_L(0); PG8_MMA(0, 0, At, B0); PG8_BAR; PG8_SCHED;
;             PG8_LDB(B1, 1, 1); PG8_STAGE(PG8_SB(1, 0), b3, voffB);
;             PG8_BAR; PG8_WAIT_L(0); PG8_MMA(0, 1, At, B1); PG8_BAR;
;             PG8_LDA(At, 1, 1); PG8_STAGE(PG8_SA(1, 0), a3, voffA);
;             PG8_BAR; PG8_WAIT_L(0); PG8_MMA(1, 0, At, B0); PG8_BAR; PG8_SCHED;
;             PG8_STAGE(PG8_SB(1, 1), b3 + hstep, voffB);
;             PG8_WAIT_V(6); PG8_BAR; PG8_MMA(1, 1, At, B1); PG8_BAR;
	s_setprio 0
	ds_read_b128 v[144:147], v241
	ds_read_b128 v[148:151], v241 offset:1024
	ds_read_b128 v[160:163], v241 offset:2048
	ds_read_b128 v[164:167], v241 offset:3072
	s_add_u32 s34, s34, s6
	s_addc_u32 s35, s35, 0
	s_mov_b32 m0, s90
	v_lshl_add_u64 v[212:213], s[34:35], 0, v[128:129]
	ds_read_b128 v[168:171], v143 offset:32768
	ds_read_b128 v[184:187], v143 offset:33792
	ds_read_b128 v[188:191], v143 offset:34816
	ds_read_b128 v[192:195], v143 offset:35840
	ds_read_b128 v[196:199], v143 offset:36864
	ds_read_b128 v[200:203], v143 offset:37888
	ds_read_b128 v[204:207], v143 offset:38912
	ds_read_b128 v[208:211], v143 offset:39936
	global_load_lds_dwordx4 v[212:213], off
	v_lshl_add_u64 v[212:213], s[34:35], 0, v[130:131]
	s_mov_b32 m0, s91
	s_nop 0
	global_load_lds_dwordx4 v[212:213], off
	s_add_i32 s17, 0, 0x1c000
	v_add_u32_e32 v183, s17, v141
	ds_read_b128 v[212:215], v183
	ds_read_b128 v[216:219], v183 offset:1024
	ds_read_b128 v[220:223], v183 offset:2048
	ds_read_b128 v[224:227], v183 offset:3072
	s_waitcnt lgkmcnt(0)
	s_setprio 1
	s_barrier
	v_mfma_f32_16x16x32_bf16 v[124:127], v[144:147], v[168:171], v[124:127]
	v_mfma_f32_16x16x32_bf16 v[120:123], v[160:163], v[168:171], v[120:123]
	v_mfma_f32_16x16x32_bf16 v[116:119], v[144:147], v[188:191], v[116:119]
	v_mfma_f32_16x16x32_bf16 v[112:115], v[160:163], v[188:191], v[112:115]
	v_mfma_f32_16x16x32_bf16 v[100:103], v[144:147], v[196:199], v[100:103]
	v_mfma_f32_16x16x32_bf16 v[96:99], v[160:163], v[196:199], v[96:99]
	v_mfma_f32_16x16x32_bf16 v[84:87], v[144:147], v[204:207], v[84:87]
	v_mfma_f32_16x16x32_bf16 v[80:83], v[160:163], v[204:207], v[80:83]
	v_mfma_f32_16x16x32_bf16 v[124:127], v[148:151], v[184:187], v[124:127]
	v_mfma_f32_16x16x32_bf16 v[120:123], v[164:167], v[184:187], v[120:123]
	v_mfma_f32_16x16x32_bf16 v[116:119], v[148:151], v[192:195], v[116:119]
	v_mfma_f32_16x16x32_bf16 v[112:115], v[164:167], v[192:195], v[112:115]
	v_mfma_f32_16x16x32_bf16 v[100:103], v[148:151], v[200:203], v[100:103]
	v_mfma_f32_16x16x32_bf16 v[96:99], v[164:167], v[200:203], v[96:99]
	v_mfma_f32_16x16x32_bf16 v[84:87], v[148:151], v[208:211], v[84:87]
	v_mfma_f32_16x16x32_bf16 v[80:83], v[164:167], v[208:211], v[80:83]
	v_mfma_f32_16x16x32_bf16 v[108:111], v[212:215], v[168:171], v[108:111]
	v_mfma_f32_16x16x32_bf16 v[104:107], v[220:223], v[168:171], v[104:107]
	v_mfma_f32_16x16x32_bf16 v[92:95], v[212:215], v[188:191], v[92:95]
	v_mfma_f32_16x16x32_bf16 v[88:91], v[220:223], v[188:191], v[88:91]
	v_mfma_f32_16x16x32_bf16 v[76:79], v[212:215], v[196:199], v[76:79]
	v_mfma_f32_16x16x32_bf16 v[72:75], v[220:223], v[196:199], v[72:75]
	v_mfma_f32_16x16x32_bf16 v[68:71], v[212:215], v[204:207], v[68:71]
	v_mfma_f32_16x16x32_bf16 v[64:67], v[220:223], v[204:207], v[64:67]
	v_mfma_f32_16x16x32_bf16 v[108:111], v[216:219], v[184:187], v[108:111]
	v_mfma_f32_16x16x32_bf16 v[104:107], v[224:227], v[184:187], v[104:107]
	v_mfma_f32_16x16x32_bf16 v[92:95], v[216:219], v[192:195], v[92:95]
	v_mfma_f32_16x16x32_bf16 v[88:91], v[224:227], v[192:195], v[88:91]
	v_mfma_f32_16x16x32_bf16 v[76:79], v[216:219], v[200:203], v[76:79]
	v_mfma_f32_16x16x32_bf16 v[72:75], v[224:227], v[200:203], v[72:75]
	v_mfma_f32_16x16x32_bf16 v[68:71], v[216:219], v[208:211], v[68:71]
	v_mfma_f32_16x16x32_bf16 v[64:67], v[224:227], v[208:211], v[64:67]
	s_barrier
	s_setprio 0
	s_add_i32 s1, s1, s85
	v_lshl_add_u64 v[152:153], v[152:153], 0, s[8:9]
	s_mov_b32 m0, s1
	global_load_lds_dwordx4 v[152:153], off
	v_lshl_add_u64 v[152:153], v[228:229], 0, s[8:9]
	s_add_i32 m0, s1, 0x2000
	s_nop 0
	global_load_lds_dwordx4 v[152:153], off
	s_mov_b32 m0, s92
	v_lshl_add_u64 v[152:153], v[230:231], 0, s[8:9]
	ds_read_b128 v[168:171], v143 offset:49152
	ds_read_b128 v[184:187], v143 offset:50176
	ds_read_b128 v[188:191], v143 offset:51200
	ds_read_b128 v[192:195], v143 offset:52224
	ds_read_b128 v[196:199], v143 offset:53248
	ds_read_b128 v[200:203], v143 offset:54272
	ds_read_b128 v[204:207], v143 offset:55296
	ds_read_b128 v[208:211], v143 offset:56320
	global_load_lds_dwordx4 v[152:153], off
	v_lshl_add_u64 v[152:153], v[232:233], 0, s[8:9]
	s_mov_b32 m0, s93
	s_nop 0
	global_load_lds_dwordx4 v[152:153], off
	s_add_i32 s1, s17, s85
	v_lshl_add_u64 v[238:239], v[234:235], 0, s[8:9]
	s_mov_b32 m0, s1
	s_nop 0
	global_load_lds_dwordx4 v[238:239], off
	v_lshl_add_u64 v[238:239], v[236:237], 0, s[8:9]
	s_add_i32 m0, s1, 0x2000
	s_nop 0
	global_load_lds_dwordx4 v[238:239], off
	s_waitcnt vmcnt(6)
	s_waitcnt lgkmcnt(0)
	s_setprio 1
	s_barrier
	v_mfma_f32_16x16x32_bf16 v[60:63], v[144:147], v[168:171], v[60:63]
	v_mfma_f32_16x16x32_bf16 v[56:59], v[160:163], v[168:171], v[56:59]
	v_mfma_f32_16x16x32_bf16 v[52:55], v[144:147], v[188:191], v[52:55]
	s_add_u32 vcc_lo, vcc_lo, 0x100
	v_mfma_f32_16x16x32_bf16 v[48:51], v[160:163], v[188:191], v[48:51]
	s_addc_u32 vcc_hi, vcc_hi, 0
	v_mfma_f32_16x16x32_bf16 v[36:39], v[144:147], v[196:199], v[36:39]
	s_add_u32 s96, s96, 0x100
	v_mfma_f32_16x16x32_bf16 v[32:35], v[160:163], v[196:199], v[32:35]
	s_addc_u32 s65, s65, 0
	v_mfma_f32_16x16x32_bf16 v[20:23], v[144:147], v[204:207], v[20:23]
	s_cmp_ge_u32 s0, s94
	v_mfma_f32_16x16x32_bf16 v[16:19], v[160:163], v[204:207], v[16:19]
	s_mov_b32 s34, s0
	v_mfma_f32_16x16x32_bf16 v[60:63], v[148:151], v[184:187], v[60:63]
	v_mfma_f32_16x16x32_bf16 v[56:59], v[164:167], v[184:187], v[56:59]
	v_mfma_f32_16x16x32_bf16 v[52:55], v[148:151], v[192:195], v[52:55]
	v_mfma_f32_16x16x32_bf16 v[48:51], v[164:167], v[192:195], v[48:51]
	v_mfma_f32_16x16x32_bf16 v[36:39], v[148:151], v[200:203], v[36:39]
	v_mfma_f32_16x16x32_bf16 v[32:35], v[164:167], v[200:203], v[32:35]
	v_mfma_f32_16x16x32_bf16 v[20:23], v[148:151], v[208:211], v[20:23]
	v_mfma_f32_16x16x32_bf16 v[16:19], v[164:167], v[208:211], v[16:19]
	v_mfma_f32_16x16x32_bf16 v[44:47], v[212:215], v[168:171], v[44:47]
	v_mfma_f32_16x16x32_bf16 v[40:43], v[220:223], v[168:171], v[40:43]
	v_mfma_f32_16x16x32_bf16 v[28:31], v[212:215], v[188:191], v[28:31]
	v_mfma_f32_16x16x32_bf16 v[24:27], v[220:223], v[188:191], v[24:27]
	v_mfma_f32_16x16x32_bf16 v[12:15], v[212:215], v[196:199], v[12:15]
	v_mfma_f32_16x16x32_bf16 v[8:11], v[220:223], v[196:199], v[8:11]
	v_mfma_f32_16x16x32_bf16 v[4:7], v[212:215], v[204:207], v[4:7]
	v_mfma_f32_16x16x32_bf16 v[0:3], v[220:223], v[204:207], v[0:3]
	v_mfma_f32_16x16x32_bf16 v[44:47], v[216:219], v[184:187], v[44:47]
	v_mfma_f32_16x16x32_bf16 v[40:43], v[224:227], v[184:187], v[40:43]
	v_mfma_f32_16x16x32_bf16 v[28:31], v[216:219], v[192:195], v[28:31]
	v_mfma_f32_16x16x32_bf16 v[24:27], v[224:227], v[192:195], v[24:27]
	v_mfma_f32_16x16x32_bf16 v[12:15], v[216:219], v[200:203], v[12:15]
	v_mfma_f32_16x16x32_bf16 v[8:11], v[224:227], v[200:203], v[8:11]
	v_mfma_f32_16x16x32_bf16 v[4:7], v[216:219], v[208:211], v[4:7]
	v_mfma_f32_16x16x32_bf16 v[0:3], v[224:227], v[208:211], v[0:3]
	s_barrier
	s_setprio 0
	s_cbranch_scc0 .LBB0_100

; #define PG8_STAGE(bufoff, gbase, voff) do { _Pragma("unroll") for (int _i = 0; _i < 2; ++_i) \
;         __builtin_amdgcn_global_load_lds((const unsigned*)((const char*)(gbase) + (voff)[_i]), (LAS unsigned*)(lds + (bufoff) + ldsw + _i * 8192), 16, 0, 0); } while (0)
; #define PG8_LDA(dst, b, h) do { _Pragma("unroll") for (int m = 0; m < 4; ++m) _Pragma("unroll") for (int k = 0; k < 2; ++k) dst[m][k] = *(const LAS bf16x8*)(lds + PG8_SA(b, h) + aoff + m * 2048 + k * 1024); } while (0)
; #define PG8_LDB(dst, b, h) do { _Pragma("unroll") for (int n = 0; n < 2; ++n) _Pragma("unroll") for (int k = 0; k < 2; ++k) dst[n][k] = *(const LAS bf16x8*)(lds + PG8_SB(b, h) + boff + n * 2048 + k * 1024); } while (0)
; #define PG8_MMA(ai, bj, At, Bt) do { __builtin_amdgcn_s_setprio(1); _Pragma("unroll") for (int m = 0; m < 4; ++m) _Pragma("unroll") for (int n = 0; n < 2; ++n) _Pragma("unroll") for (int k = 0; k < 2; ++k) \
;         acc[ai][bj][m][n] = __builtin_amdgcn_mfma_f32_16x16x32_bf16(Bt[n][k], At[m][k], acc[ai][bj][m][n], 0, 0, 0); __builtin_amdgcn_s_setprio(0); } while (0)
; template <class Epi, class Sched>
; __device__ __forceinline__ void gemm_phase(LAS unsigned char* lds, const Gemm g, const Sched& S, const Epi& E, int tid) {
;     ...
;         const bool has_next = S.next(ui + 1, nxt);
;         const char* nA = has_next ? (const char*)g.A + (size_t)nxt.pm * tstep : cA; const char* nB = has_next ? (const char*)g.Bt + (size_t)nxt.pn * tstep : cB;
;         for (int t = 0; t < nt; t += 2) {
;             const bool last = (t == nt - 2);
;             const char* a1 = cA + (size_t)(t + 1) * kstep;
;             const char* a2 = last ? nA : cA + (size_t)(t + 2) * kstep; const char* b2 = last ? nB : cB + (size_t)(t + 2) * kstep;
;             const char* a3 = a2 + kstep; const char* b3 = b2 + kstep;
;             PG8_LDB(B0, 0, 0); PG8_SCHED; PG8_LDA(At, 0, 0); PG8_STAGE(PG8_SA(1, 1), a1 + hstep, voffA);
;             PG8_WAIT_L(8); PG8_BAR; PG8_WAIT_L(0); PG8_MMA(0, 0, At, B0); PG8_BAR; PG8_SCHED;
;             PG8_LDB(B1, 0, 1); PG8_STAGE(PG8_SB(0, 0), b2, voffB);
;             PG8_BAR; PG8_WAIT_L(0); PG8_MMA(0, 1, At, B1); PG8_BAR;
;             PG8_LDA(At, 0, 1); PG8_STAGE(PG8_SA(0, 0), a2, voffA);
;             PG8_BAR; PG8_WAIT_L(0); PG8_MMA(1, 0, At, B0); PG8_BAR; PG8_SCHED;
;             PG8_STAGE(PG8_SB(0, 1), b2 + hstep, voffB);
.LBB0_114:
	s_ashr_i32 s25, s24, 31
	s_lshl_b64 s[0:1], s[24:25], 19
	v_cmp_lt_i64_e32 vcc, s[28:29], v[158:159]
	s_add_u32 s28, s26, s0
	s_addc_u32 s29, s27, s1
	s_and_b64 s[0:1], vcc, exec
	s_cselect_b32 s25, s29, s41
	s_cselect_b32 s53, s28, s40
	s_ashr_i32 s15, s14, 31
	s_lshl_b64 s[0:1], s[14:15], 19
	s_add_u32 s30, s19, s0
	s_addc_u32 s31, s44, s1
	s_and_b64 s[0:1], vcc, exec
	s_cselect_b32 s15, s31, s43
	s_cselect_b32 s55, s30, s42
	s_add_u32 s40, s40, 0x40080
	s_addc_u32 s41, s41, 0
	s_add_u32 s58, s42, 0x100
	s_addc_u32 s60, s43, 0
	s_mov_b32 s61, -2
	s_add_u32 s0, s40, 0xfffc0080
	s_addc_u32 s1, s41, -1
	s_add_i32 s17, 0, 0x10000
	v_add_u32_e32 v160, s17, v143
	ds_read_b128 v[138:141], v160
	ds_read_b128 v[146:149], v160 offset:1024
	ds_read_b128 v[150:153], v160 offset:2048
	ds_read_b128 v[160:163], v160 offset:3072
	s_cmp_eq_u32 s61, 12
	s_cselect_b32 s43, s25, s1
	s_cselect_b32 s42, s53, s0
	s_cselect_b32 s35, s15, s60
	s_cselect_b32 s34, s55, s58
	v_lshl_add_u64 v[208:209], s[40:41], 0, v[134:135]
	s_add_i32 m0, s39, 0xc000
	ds_read_b128 v[164:167], v145
	ds_read_b128 v[168:171], v145 offset:1024
	ds_read_b128 v[184:187], v145 offset:2048
	ds_read_b128 v[188:191], v145 offset:3072
	ds_read_b128 v[192:195], v145 offset:4096
	ds_read_b128 v[196:199], v145 offset:5120
	ds_read_b128 v[200:203], v145 offset:6144
	ds_read_b128 v[204:207], v145 offset:7168
	global_load_lds_dwordx4 v[208:209], off
	v_lshl_add_u64 v[208:209], s[40:41], 0, v[136:137]
	s_add_i32 m0, s39, 0xe000
	s_nop 0
	global_load_lds_dwordx4 v[208:209], off
	s_add_i32 s63, 0, 0x14000
	v_add_u32_e32 v183, s63, v143
	ds_read_b128 v[208:211], v183
	ds_read_b128 v[212:215], v183 offset:1024
	ds_read_b128 v[216:219], v183 offset:2048
	ds_read_b128 v[220:223], v183 offset:3072
	s_waitcnt lgkmcnt(0)
	s_setprio 1
	s_barrier
	v_mfma_f32_16x16x32_bf16 v[124:127], v[138:141], v[164:167], 0
	v_mfma_f32_16x16x32_bf16 v[120:123], v[150:153], v[164:167], 0
	v_mfma_f32_16x16x32_bf16 v[108:111], v[138:141], v[184:187], 0
	v_mfma_f32_16x16x32_bf16 v[104:107], v[150:153], v[184:187], 0
	v_mfma_f32_16x16x32_bf16 v[92:95], v[138:141], v[192:195], 0
	v_mfma_f32_16x16x32_bf16 v[88:91], v[150:153], v[192:195], 0
	v_mfma_f32_16x16x32_bf16 v[76:79], v[138:141], v[200:203], 0
	v_mfma_f32_16x16x32_bf16 v[72:75], v[150:153], v[200:203], 0
	v_mfma_f32_16x16x32_bf16 v[124:127], v[146:149], v[168:171], v[124:127]
	v_mfma_f32_16x16x32_bf16 v[120:123], v[160:163], v[168:171], v[120:123]
	v_mfma_f32_16x16x32_bf16 v[108:111], v[146:149], v[188:191], v[108:111]
	v_mfma_f32_16x16x32_bf16 v[104:107], v[160:163], v[188:191], v[104:107]
	v_mfma_f32_16x16x32_bf16 v[92:95], v[146:149], v[196:199], v[92:95]
	v_mfma_f32_16x16x32_bf16 v[88:91], v[160:163], v[196:199], v[88:91]
	v_mfma_f32_16x16x32_bf16 v[76:79], v[146:149], v[204:207], v[76:79]
	v_mfma_f32_16x16x32_bf16 v[72:75], v[160:163], v[204:207], v[72:75]
	v_mfma_f32_16x16x32_bf16 v[116:119], v[208:211], v[164:167], 0
	v_mfma_f32_16x16x32_bf16 v[112:115], v[216:219], v[164:167], 0
	v_mfma_f32_16x16x32_bf16 v[100:103], v[208:211], v[184:187], 0
	v_mfma_f32_16x16x32_bf16 v[96:99], v[216:219], v[184:187], 0
	v_mfma_f32_16x16x32_bf16 v[84:87], v[208:211], v[192:195], 0
	v_mfma_f32_16x16x32_bf16 v[80:83], v[216:219], v[192:195], 0
	v_mfma_f32_16x16x32_bf16 v[68:71], v[208:211], v[200:203], 0
	v_mfma_f32_16x16x32_bf16 v[64:67], v[216:219], v[200:203], 0
	v_mfma_f32_16x16x32_bf16 v[116:119], v[212:215], v[168:171], v[116:119]
	v_mfma_f32_16x16x32_bf16 v[112:115], v[220:223], v[168:171], v[112:115]
	v_mfma_f32_16x16x32_bf16 v[100:103], v[212:215], v[188:191], v[100:103]
	v_mfma_f32_16x16x32_bf16 v[96:99], v[220:223], v[188:191], v[96:99]
	v_mfma_f32_16x16x32_bf16 v[84:87], v[212:215], v[196:199], v[84:87]
	v_mfma_f32_16x16x32_bf16 v[80:83], v[220:223], v[196:199], v[80:83]
	v_mfma_f32_16x16x32_bf16 v[68:71], v[212:215], v[204:207], v[68:71]
	v_mfma_f32_16x16x32_bf16 v[64:67], v[220:223], v[204:207], v[64:67]
	s_barrier
	s_setprio 0
	s_add_i32 s0, s17, s45
	v_lshl_add_u64 v[224:225], s[34:35], 0, v[154:155]
	s_mov_b32 m0, s0
	global_load_lds_dwordx4 v[224:225], off
	v_lshl_add_u64 v[226:227], s[34:35], 0, v[128:129]
	s_add_i32 m0, s0, 0x2000
	s_nop 0
	global_load_lds_dwordx4 v[226:227], off
	s_mov_b32 m0, s39
	v_lshl_add_u64 v[228:229], s[42:43], 0, v[132:133]
	ds_read_b128 v[164:167], v145 offset:16384
	ds_read_b128 v[168:171], v145 offset:17408
	ds_read_b128 v[184:187], v145 offset:18432
	ds_read_b128 v[188:191], v145 offset:19456
	ds_read_b128 v[192:195], v145 offset:20480
	ds_read_b128 v[196:199], v145 offset:21504
	ds_read_b128 v[200:203], v145 offset:22528
	ds_read_b128 v[204:207], v145 offset:23552
	global_load_lds_dwordx4 v[228:229], off
	v_lshl_add_u64 v[230:231], s[42:43], 0, v[130:131]
	s_mov_b32 m0, s47
	s_nop 0
	global_load_lds_dwordx4 v[230:231], off
	s_add_u32 s0, s34, 0x40000
	s_addc_u32 s1, s35, 0
	s_add_i32 s17, s63, s45
	v_lshl_add_u64 v[238:239], s[0:1], 0, v[154:155]
	s_mov_b32 m0, s17
	s_nop 0
	global_load_lds_dwordx4 v[238:239], off
	v_lshl_add_u64 v[238:239], s[0:1], 0, v[128:129]
	s_add_i32 m0, s17, 0x2000
	s_nop 0
	global_load_lds_dwordx4 v[238:239], off
	s_waitcnt vmcnt(16)
	s_waitcnt lgkmcnt(0)
	s_setprio 1
	s_barrier
; #define PG8_STAGE(bufoff, gbase, voff) do { _Pragma("unroll") for (int _i = 0; _i < 2; ++_i) \
;         __builtin_amdgcn_global_load_lds((const unsigned*)((const char*)(gbase) + (voff)[_i]), (LAS unsigned*)(lds + (bufoff) + ldsw + _i * 8192), 16, 0, 0); } while (0)
; #define PG8_LDA(dst, b, h) do { _Pragma("unroll") for (int m = 0; m < 4; ++m) _Pragma("unroll") for (int k = 0; k < 2; ++k) dst[m][k] = *(const LAS bf16x8*)(lds + PG8_SA(b, h) + aoff + m * 2048 + k * 1024); } while (0)
; #define PG8_LDB(dst, b, h) do { _Pragma("unroll") for (int n = 0; n < 2; ++n) _Pragma("unroll") for (int k = 0; k < 2; ++k) dst[n][k] = *(const LAS bf16x8*)(lds + PG8_SB(b, h) + boff + n * 2048 + k * 1024); } while (0)
; #define PG8_MMA(ai, bj, At, Bt) do { __builtin_amdgcn_s_setprio(1); _Pragma("unroll") for (int m = 0; m < 4; ++m) _Pragma("unroll") for (int n = 0; n < 2; ++n) _Pragma("unroll") for (int k = 0; k < 2; ++k) \
;         acc[ai][bj][m][n] = __builtin_amdgcn_mfma_f32_16x16x32_bf16(Bt[n][k], At[m][k], acc[ai][bj][m][n], 0, 0, 0); __builtin_amdgcn_s_setprio(0); } while (0)
; #define PG8_WAIT_V(n) asm volatile("s_waitcnt vmcnt(" #n ")" ::: "memory")
; #define PG8_WAIT_L(n) asm volatile("s_waitcnt lgkmcnt(" #n ")" ::: "memory")
; #define PG8_BAR __builtin_amdgcn_s_barrier()
; #define PG8_SCHED __builtin_amdgcn_sched_barrier(0)
; template <class Epi, class Sched>
; __device__ __forceinline__ void gemm_phase(LAS unsigned char* lds, const Gemm g, const Sched& S, const Epi& E, int tid) {
;     ...
;             PG8_BAR; PG8_WAIT_L(0); PG8_MMA(1, 0, At, B0); PG8_BAR; PG8_SCHED;
;             PG8_STAGE(PG8_SB(0, 1), b2 + hstep, voffB);
;             PG8_WAIT_V(6); PG8_BAR; PG8_MMA(1, 1, At, B1); PG8_BAR;
;             PG8_LDB(B0, 1, 0); PG8_SCHED; PG8_LDA(At, 1, 0); PG8_STAGE(PG8_SA(0, 1), a2 + hstep, voffA);
;             PG8_WAIT_L(8); PG8_BAR; PG8_WAIT_L(0); PG8_MMA(0, 0, At, B0); PG8_BAR; PG8_SCHED;
;             PG8_LDB(B1, 1, 1); PG8_STAGE(PG8_SB(1, 0), b3, voffB);
;             PG8_BAR; PG8_WAIT_L(0); PG8_MMA(0, 1, At, B1); PG8_BAR;
	v_mfma_f32_16x16x32_bf16 v[60:63], v[138:141], v[164:167], 0
	v_mfma_f32_16x16x32_bf16 v[56:59], v[150:153], v[164:167], 0
	v_mfma_f32_16x16x32_bf16 v[44:47], v[138:141], v[184:187], 0
	s_add_i32 s17, 0, 0x18000
	v_mfma_f32_16x16x32_bf16 v[40:43], v[150:153], v[184:187], 0
	v_add_u32_e32 v241, s17, v143
	v_mfma_f32_16x16x32_bf16 v[28:31], v[138:141], v[192:195], 0
	v_mfma_f32_16x16x32_bf16 v[24:27], v[150:153], v[192:195], 0
	v_mfma_f32_16x16x32_bf16 v[12:15], v[138:141], v[200:203], 0
	v_mfma_f32_16x16x32_bf16 v[8:11], v[150:153], v[200:203], 0
	v_mfma_f32_16x16x32_bf16 v[60:63], v[146:149], v[168:171], v[60:63]
	v_mfma_f32_16x16x32_bf16 v[56:59], v[160:163], v[168:171], v[56:59]
	v_mfma_f32_16x16x32_bf16 v[44:47], v[146:149], v[188:191], v[44:47]
	v_mfma_f32_16x16x32_bf16 v[40:43], v[160:163], v[188:191], v[40:43]
	v_mfma_f32_16x16x32_bf16 v[28:31], v[146:149], v[196:199], v[28:31]
	v_mfma_f32_16x16x32_bf16 v[24:27], v[160:163], v[196:199], v[24:27]
	v_mfma_f32_16x16x32_bf16 v[12:15], v[146:149], v[204:207], v[12:15]
	v_mfma_f32_16x16x32_bf16 v[8:11], v[160:163], v[204:207], v[8:11]
	v_mfma_f32_16x16x32_bf16 v[52:55], v[208:211], v[164:167], 0
	v_mfma_f32_16x16x32_bf16 v[48:51], v[216:219], v[164:167], 0
	v_mfma_f32_16x16x32_bf16 v[36:39], v[208:211], v[184:187], 0
	v_mfma_f32_16x16x32_bf16 v[32:35], v[216:219], v[184:187], 0
	v_mfma_f32_16x16x32_bf16 v[20:23], v[208:211], v[192:195], 0
	v_mfma_f32_16x16x32_bf16 v[16:19], v[216:219], v[192:195], 0
	v_mfma_f32_16x16x32_bf16 v[4:7], v[208:211], v[200:203], 0
	v_mfma_f32_16x16x32_bf16 v[0:3], v[216:219], v[200:203], 0
	v_mfma_f32_16x16x32_bf16 v[52:55], v[212:215], v[168:171], v[52:55]
	v_mfma_f32_16x16x32_bf16 v[48:51], v[220:223], v[168:171], v[48:51]
	v_mfma_f32_16x16x32_bf16 v[36:39], v[212:215], v[188:191], v[36:39]
	v_mfma_f32_16x16x32_bf16 v[32:35], v[220:223], v[188:191], v[32:35]
	v_mfma_f32_16x16x32_bf16 v[20:23], v[212:215], v[196:199], v[20:23]
	v_mfma_f32_16x16x32_bf16 v[16:19], v[220:223], v[196:199], v[16:19]
	v_mfma_f32_16x16x32_bf16 v[4:7], v[212:215], v[204:207], v[4:7]
	v_mfma_f32_16x16x32_bf16 v[0:3], v[220:223], v[204:207], v[0:3]
	s_barrier
	s_setprio 0
	ds_read_b128 v[138:141], v241
	ds_read_b128 v[146:149], v241 offset:1024
	ds_read_b128 v[150:153], v241 offset:2048
	ds_read_b128 v[160:163], v241 offset:3072
	s_add_u32 s0, s42, 0x40000
	s_addc_u32 s1, s43, 0
	s_mov_b32 m0, s48
	v_lshl_add_u64 v[208:209], s[0:1], 0, v[132:133]
	ds_read_b128 v[164:167], v145 offset:32768
	ds_read_b128 v[168:171], v145 offset:33792
	ds_read_b128 v[184:187], v145 offset:34816
	ds_read_b128 v[188:191], v145 offset:35840
	ds_read_b128 v[192:195], v145 offset:36864
	ds_read_b128 v[196:199], v145 offset:37888
	ds_read_b128 v[200:203], v145 offset:38912
	ds_read_b128 v[204:207], v145 offset:39936
	global_load_lds_dwordx4 v[208:209], off
	v_lshl_add_u64 v[208:209], s[0:1], 0, v[130:131]
	s_mov_b32 m0, s49
	s_nop 0
	global_load_lds_dwordx4 v[208:209], off
	s_add_i32 s42, 0, 0x1c000
	v_add_u32_e32 v183, s42, v143
	ds_read_b128 v[208:211], v183
	ds_read_b128 v[212:215], v183 offset:1024
	ds_read_b128 v[216:219], v183 offset:2048
	ds_read_b128 v[220:223], v183 offset:3072
	s_waitcnt vmcnt(8)
	s_waitcnt lgkmcnt(0)
	s_setprio 1
	s_barrier
	v_mfma_f32_16x16x32_bf16 v[124:127], v[138:141], v[164:167], v[124:127]
	v_mfma_f32_16x16x32_bf16 v[120:123], v[150:153], v[164:167], v[120:123]
	v_mfma_f32_16x16x32_bf16 v[108:111], v[138:141], v[184:187], v[108:111]
	v_mfma_f32_16x16x32_bf16 v[104:107], v[150:153], v[184:187], v[104:107]
	v_mfma_f32_16x16x32_bf16 v[92:95], v[138:141], v[192:195], v[92:95]
	v_mfma_f32_16x16x32_bf16 v[88:91], v[150:153], v[192:195], v[88:91]
	v_mfma_f32_16x16x32_bf16 v[76:79], v[138:141], v[200:203], v[76:79]
	v_mfma_f32_16x16x32_bf16 v[72:75], v[150:153], v[200:203], v[72:75]
	v_mfma_f32_16x16x32_bf16 v[124:127], v[146:149], v[168:171], v[124:127]
	v_mfma_f32_16x16x32_bf16 v[120:123], v[160:163], v[168:171], v[120:123]
	v_mfma_f32_16x16x32_bf16 v[108:111], v[146:149], v[188:191], v[108:111]
	v_mfma_f32_16x16x32_bf16 v[104:107], v[160:163], v[188:191], v[104:107]
	v_mfma_f32_16x16x32_bf16 v[92:95], v[146:149], v[196:199], v[92:95]
	v_mfma_f32_16x16x32_bf16 v[88:91], v[160:163], v[196:199], v[88:91]
	v_mfma_f32_16x16x32_bf16 v[76:79], v[146:149], v[204:207], v[76:79]
	v_mfma_f32_16x16x32_bf16 v[72:75], v[160:163], v[204:207], v[72:75]
	v_mfma_f32_16x16x32_bf16 v[116:119], v[208:211], v[164:167], v[116:119]
	v_mfma_f32_16x16x32_bf16 v[112:115], v[216:219], v[164:167], v[112:115]
	v_mfma_f32_16x16x32_bf16 v[100:103], v[208:211], v[184:187], v[100:103]
	v_mfma_f32_16x16x32_bf16 v[96:99], v[216:219], v[184:187], v[96:99]
	v_mfma_f32_16x16x32_bf16 v[84:87], v[208:211], v[192:195], v[84:87]
	v_mfma_f32_16x16x32_bf16 v[80:83], v[216:219], v[192:195], v[80:83]
	v_mfma_f32_16x16x32_bf16 v[68:71], v[208:211], v[200:203], v[68:71]
	v_mfma_f32_16x16x32_bf16 v[64:67], v[216:219], v[200:203], v[64:67]
	v_mfma_f32_16x16x32_bf16 v[116:119], v[212:215], v[168:171], v[116:119]
	v_mfma_f32_16x16x32_bf16 v[112:115], v[220:223], v[168:171], v[112:115]
	v_mfma_f32_16x16x32_bf16 v[100:103], v[212:215], v[188:191], v[100:103]
	v_mfma_f32_16x16x32_bf16 v[96:99], v[220:223], v[188:191], v[96:99]
	v_mfma_f32_16x16x32_bf16 v[84:87], v[212:215], v[196:199], v[84:87]
	v_mfma_f32_16x16x32_bf16 v[80:83], v[220:223], v[196:199], v[80:83]
	v_mfma_f32_16x16x32_bf16 v[68:71], v[212:215], v[204:207], v[68:71]
	v_mfma_f32_16x16x32_bf16 v[64:67], v[220:223], v[204:207], v[64:67]
	s_barrier
; #define PG8_STAGE(bufoff, gbase, voff) do { _Pragma("unroll") for (int _i = 0; _i < 2; ++_i) \
;         __builtin_amdgcn_global_load_lds((const unsigned*)((const char*)(gbase) + (voff)[_i]), (LAS unsigned*)(lds + (bufoff) + ldsw + _i * 8192), 16, 0, 0); } while (0)
; #define PG8_LDA(dst, b, h) do { _Pragma("unroll") for (int m = 0; m < 4; ++m) _Pragma("unroll") for (int k = 0; k < 2; ++k) dst[m][k] = *(const LAS bf16x8*)(lds + PG8_SA(b, h) + aoff + m * 2048 + k * 1024); } while (0)
; #define PG8_LDB(dst, b, h) do { _Pragma("unroll") for (int n = 0; n < 2; ++n) _Pragma("unroll") for (int k = 0; k < 2; ++k) dst[n][k] = *(const LAS bf16x8*)(lds + PG8_SB(b, h) + boff + n * 2048 + k * 1024); } while (0)
; #define PG8_MMA(ai, bj, At, Bt) do { __builtin_amdgcn_s_setprio(1); _Pragma("unroll") for (int m = 0; m < 4; ++m) _Pragma("unroll") for (int n = 0; n < 2; ++n) _Pragma("unroll") for (int k = 0; k < 2; ++k) \
;         acc[ai][bj][m][n] = __builtin_amdgcn_mfma_f32_16x16x32_bf16(Bt[n][k], At[m][k], acc[ai][bj][m][n], 0, 0, 0); __builtin_amdgcn_s_setprio(0); } while (0)
; #define PG8_WAIT_V(n) asm volatile("s_waitcnt vmcnt(" #n ")" ::: "memory")
; #define PG8_WAIT_L(n) asm volatile("s_waitcnt lgkmcnt(" #n ")" ::: "memory")
; #define PG8_BAR __builtin_amdgcn_s_barrier()
; #define PG8_SCHED __builtin_amdgcn_sched_barrier(0)
; template <class Epi, class Sched>
; __device__ __forceinline__ void gemm_phase(LAS unsigned char* lds, const Gemm g, const Sched& S, const Epi& E, int tid) {
;     ...
;             PG8_LDB(B0, 0, 0); PG8_SCHED; PG8_LDA(At, 0, 0); PG8_STAGE(PG8_SA(1, 1), a1 + hstep, voffA);
;             PG8_WAIT_L(8); PG8_BAR; PG8_WAIT_L(0); PG8_MMA(0, 0, At, B0); PG8_BAR; PG8_SCHED;
;             PG8_LDB(B1, 0, 1); PG8_STAGE(PG8_SB(0, 0), b2, voffB);
;     ...
;             PG8_LDA(At, 1, 1); PG8_STAGE(PG8_SA(1, 0), a3, voffA);
;             PG8_BAR; PG8_WAIT_L(0); PG8_MMA(1, 0, At, B0); PG8_BAR; PG8_SCHED;
;             PG8_STAGE(PG8_SB(1, 1), b3 + hstep, voffB);
;             PG8_WAIT_V(6); PG8_BAR; PG8_MMA(1, 1, At, B1); PG8_BAR;
	s_setprio 0
	s_add_i32 s0, s17, s45
	v_lshl_add_u64 v[224:225], v[224:225], 0, s[8:9]
	s_mov_b32 m0, s0
	global_load_lds_dwordx4 v[224:225], off
	v_lshl_add_u64 v[224:225], v[226:227], 0, s[8:9]
	s_add_i32 m0, s0, 0x2000
	s_nop 0
	global_load_lds_dwordx4 v[224:225], off
	s_mov_b32 m0, s6
	v_lshl_add_u64 v[224:225], v[228:229], 0, s[8:9]
	ds_read_b128 v[164:167], v145 offset:49152
	ds_read_b128 v[168:171], v145 offset:50176
	ds_read_b128 v[184:187], v145 offset:51200
	ds_read_b128 v[188:191], v145 offset:52224
	ds_read_b128 v[192:195], v145 offset:53248
	ds_read_b128 v[196:199], v145 offset:54272
	ds_read_b128 v[200:203], v145 offset:55296
	ds_read_b128 v[204:207], v145 offset:56320
	global_load_lds_dwordx4 v[224:225], off
	v_lshl_add_u64 v[224:225], v[230:231], 0, s[8:9]
	s_mov_b32 m0, s50
	s_nop 0
	global_load_lds_dwordx4 v[224:225], off
	s_add_u32 s0, s34, 0x40080
	s_addc_u32 s1, s35, 0
	s_add_i32 s17, s42, s45
	v_lshl_add_u64 v[238:239], s[0:1], 0, v[154:155]
	s_mov_b32 m0, s17
	s_nop 0
	global_load_lds_dwordx4 v[238:239], off
	v_lshl_add_u64 v[238:239], s[0:1], 0, v[128:129]
	s_add_i32 m0, s17, 0x2000
	s_nop 0
	global_load_lds_dwordx4 v[238:239], off
	s_waitcnt vmcnt(6)
	s_waitcnt lgkmcnt(0)
	s_setprio 1
	s_barrier
	v_mfma_f32_16x16x32_bf16 v[60:63], v[138:141], v[164:167], v[60:63]
	v_mfma_f32_16x16x32_bf16 v[56:59], v[150:153], v[164:167], v[56:59]
	v_mfma_f32_16x16x32_bf16 v[44:47], v[138:141], v[184:187], v[44:47]
	s_add_i32 s61, s61, 2
	v_mfma_f32_16x16x32_bf16 v[40:43], v[150:153], v[184:187], v[40:43]
	s_add_u32 s40, s40, 0x100
	v_mfma_f32_16x16x32_bf16 v[28:31], v[138:141], v[192:195], v[28:31]
	s_addc_u32 s41, s41, 0
	v_mfma_f32_16x16x32_bf16 v[24:27], v[150:153], v[192:195], v[24:27]
	s_add_u32 s58, s58, 0x100
	v_mfma_f32_16x16x32_bf16 v[12:15], v[138:141], v[200:203], v[12:15]
	s_addc_u32 s60, s60, 0
	v_mfma_f32_16x16x32_bf16 v[8:11], v[150:153], v[200:203], v[8:11]
	s_cmp_gt_u32 s61, 13
	v_mfma_f32_16x16x32_bf16 v[60:63], v[146:149], v[168:171], v[60:63]
	v_mfma_f32_16x16x32_bf16 v[56:59], v[160:163], v[168:171], v[56:59]
	v_mfma_f32_16x16x32_bf16 v[44:47], v[146:149], v[188:191], v[44:47]
	v_mfma_f32_16x16x32_bf16 v[40:43], v[160:163], v[188:191], v[40:43]
	v_mfma_f32_16x16x32_bf16 v[28:31], v[146:149], v[196:199], v[28:31]
	v_mfma_f32_16x16x32_bf16 v[24:27], v[160:163], v[196:199], v[24:27]
	v_mfma_f32_16x16x32_bf16 v[12:15], v[146:149], v[204:207], v[12:15]
	v_mfma_f32_16x16x32_bf16 v[8:11], v[160:163], v[204:207], v[8:11]
	v_mfma_f32_16x16x32_bf16 v[52:55], v[208:211], v[164:167], v[52:55]
	v_mfma_f32_16x16x32_bf16 v[48:51], v[216:219], v[164:167], v[48:51]
	v_mfma_f32_16x16x32_bf16 v[36:39], v[208:211], v[184:187], v[36:39]
	v_mfma_f32_16x16x32_bf16 v[32:35], v[216:219], v[184:187], v[32:35]
	v_mfma_f32_16x16x32_bf16 v[20:23], v[208:211], v[192:195], v[20:23]
	v_mfma_f32_16x16x32_bf16 v[16:19], v[216:219], v[192:195], v[16:19]
	v_mfma_f32_16x16x32_bf16 v[4:7], v[208:211], v[200:203], v[4:7]
	v_mfma_f32_16x16x32_bf16 v[0:3], v[216:219], v[200:203], v[0:3]
	v_mfma_f32_16x16x32_bf16 v[52:55], v[212:215], v[168:171], v[52:55]
	v_mfma_f32_16x16x32_bf16 v[48:51], v[220:223], v[168:171], v[48:51]
	v_mfma_f32_16x16x32_bf16 v[36:39], v[212:215], v[188:191], v[36:39]
	v_mfma_f32_16x16x32_bf16 v[32:35], v[220:223], v[188:191], v[32:35]
	v_mfma_f32_16x16x32_bf16 v[20:23], v[212:215], v[196:199], v[20:23]
	v_mfma_f32_16x16x32_bf16 v[16:19], v[220:223], v[196:199], v[16:19]
	v_mfma_f32_16x16x32_bf16 v[4:7], v[212:215], v[204:207], v[4:7]
	v_mfma_f32_16x16x32_bf16 v[0:3], v[220:223], v[204:207], v[0:3]
	s_barrier
	s_setprio 0
	s_cbranch_scc1 .Lpeel_exit_swiglu
.LBB0_115:
	s_add_u32 s0, s40, 0xfffc0080
	s_addc_u32 s1, s41, -1
	s_add_i32 s17, 0, 0x10000
	v_add_u32_e32 v160, s17, v143
	ds_read_b128 v[138:141], v160
	ds_read_b128 v[146:149], v160 offset:1024
	ds_read_b128 v[150:153], v160 offset:2048
	ds_read_b128 v[160:163], v160 offset:3072
	s_cmp_eq_u32 s61, 12
	s_cselect_b32 s43, s25, s1
	s_cselect_b32 s42, s53, s0
	s_cselect_b32 s35, s15, s60
	s_cselect_b32 s34, s55, s58
	v_lshl_add_u64 v[208:209], s[40:41], 0, v[134:135]
	s_add_i32 m0, s39, 0xc000
	ds_read_b128 v[164:167], v145
	ds_read_b128 v[168:171], v145 offset:1024
	ds_read_b128 v[184:187], v145 offset:2048
	ds_read_b128 v[188:191], v145 offset:3072
	ds_read_b128 v[192:195], v145 offset:4096
	ds_read_b128 v[196:199], v145 offset:5120
	ds_read_b128 v[200:203], v145 offset:6144
	ds_read_b128 v[204:207], v145 offset:7168
	global_load_lds_dwordx4 v[208:209], off
	v_lshl_add_u64 v[208:209], s[40:41], 0, v[136:137]
	s_add_i32 m0, s39, 0xe000
	s_nop 0
	global_load_lds_dwordx4 v[208:209], off
	s_add_i32 s63, 0, 0x14000
	v_add_u32_e32 v183, s63, v143
	ds_read_b128 v[208:211], v183
	ds_read_b128 v[212:215], v183 offset:1024
	ds_read_b128 v[216:219], v183 offset:2048
	ds_read_b128 v[220:223], v183 offset:3072
	s_waitcnt lgkmcnt(0)
	s_setprio 1
	s_barrier
; #define PG8_STAGE(bufoff, gbase, voff) do { _Pragma("unroll") for (int _i = 0; _i < 2; ++_i) \
;         __builtin_amdgcn_global_load_lds((const unsigned*)((const char*)(gbase) + (voff)[_i]), (LAS unsigned*)(lds + (bufoff) + ldsw + _i * 8192), 16, 0, 0); } while (0)
; #define PG8_LDA(dst, b, h) do { _Pragma("unroll") for (int m = 0; m < 4; ++m) _Pragma("unroll") for (int k = 0; k < 2; ++k) dst[m][k] = *(const LAS bf16x8*)(lds + PG8_SA(b, h) + aoff + m * 2048 + k * 1024); } while (0)
; #define PG8_LDB(dst, b, h) do { _Pragma("unroll") for (int n = 0; n < 2; ++n) _Pragma("unroll") for (int k = 0; k < 2; ++k) dst[n][k] = *(const LAS bf16x8*)(lds + PG8_SB(b, h) + boff + n * 2048 + k * 1024); } while (0)
; #define PG8_MMA(ai, bj, At, Bt) do { __builtin_amdgcn_s_setprio(1); _Pragma("unroll") for (int m = 0; m < 4; ++m) _Pragma("unroll") for (int n = 0; n < 2; ++n) _Pragma("unroll") for (int k = 0; k < 2; ++k) \
;         acc[ai][bj][m][n] = __builtin_amdgcn_mfma_f32_16x16x32_bf16(Bt[n][k], At[m][k], acc[ai][bj][m][n], 0, 0, 0); __builtin_amdgcn_s_setprio(0); } while (0)
; #define PG8_WAIT_V(n) asm volatile("s_waitcnt vmcnt(" #n ")" ::: "memory")
; #define PG8_WAIT_L(n) asm volatile("s_waitcnt lgkmcnt(" #n ")" ::: "memory")
; #define PG8_BAR __builtin_amdgcn_s_barrier()
; #define PG8_SCHED __builtin_amdgcn_sched_barrier(0)
; template <class Epi, class Sched>
; __device__ __forceinline__ void gemm_phase(LAS unsigned char* lds, const Gemm g, const Sched& S, const Epi& E, int tid) {
;     ...
;             PG8_LDB(B0, 0, 0); PG8_SCHED; PG8_LDA(At, 0, 0); PG8_STAGE(PG8_SA(1, 1), a1 + hstep, voffA);
;             PG8_WAIT_L(8); PG8_BAR; PG8_WAIT_L(0); PG8_MMA(0, 0, At, B0); PG8_BAR; PG8_SCHED;
;             PG8_LDB(B1, 0, 1); PG8_STAGE(PG8_SB(0, 0), b2, voffB);
;             PG8_BAR; PG8_WAIT_L(0); PG8_MMA(0, 1, At, B1); PG8_BAR;
;             PG8_LDA(At, 0, 1); PG8_STAGE(PG8_SA(0, 0), a2, voffA);
;             PG8_BAR; PG8_WAIT_L(0); PG8_MMA(1, 0, At, B0); PG8_BAR; PG8_SCHED;
;             PG8_STAGE(PG8_SB(0, 1), b2 + hstep, voffB);
;             PG8_WAIT_V(6); PG8_BAR; PG8_MMA(1, 1, At, B1); PG8_BAR;
	v_mfma_f32_16x16x32_bf16 v[124:127], v[138:141], v[164:167], v[124:127]
	v_mfma_f32_16x16x32_bf16 v[120:123], v[150:153], v[164:167], v[120:123]
	v_mfma_f32_16x16x32_bf16 v[108:111], v[138:141], v[184:187], v[108:111]
	v_mfma_f32_16x16x32_bf16 v[104:107], v[150:153], v[184:187], v[104:107]
	v_mfma_f32_16x16x32_bf16 v[92:95], v[138:141], v[192:195], v[92:95]
	v_mfma_f32_16x16x32_bf16 v[88:91], v[150:153], v[192:195], v[88:91]
	v_mfma_f32_16x16x32_bf16 v[76:79], v[138:141], v[200:203], v[76:79]
	v_mfma_f32_16x16x32_bf16 v[72:75], v[150:153], v[200:203], v[72:75]
	v_mfma_f32_16x16x32_bf16 v[124:127], v[146:149], v[168:171], v[124:127]
	v_mfma_f32_16x16x32_bf16 v[120:123], v[160:163], v[168:171], v[120:123]
	v_mfma_f32_16x16x32_bf16 v[108:111], v[146:149], v[188:191], v[108:111]
	v_mfma_f32_16x16x32_bf16 v[104:107], v[160:163], v[188:191], v[104:107]
	v_mfma_f32_16x16x32_bf16 v[92:95], v[146:149], v[196:199], v[92:95]
	v_mfma_f32_16x16x32_bf16 v[88:91], v[160:163], v[196:199], v[88:91]
	v_mfma_f32_16x16x32_bf16 v[76:79], v[146:149], v[204:207], v[76:79]
	v_mfma_f32_16x16x32_bf16 v[72:75], v[160:163], v[204:207], v[72:75]
	v_mfma_f32_16x16x32_bf16 v[116:119], v[208:211], v[164:167], v[116:119]
	v_mfma_f32_16x16x32_bf16 v[112:115], v[216:219], v[164:167], v[112:115]
	v_mfma_f32_16x16x32_bf16 v[100:103], v[208:211], v[184:187], v[100:103]
	v_mfma_f32_16x16x32_bf16 v[96:99], v[216:219], v[184:187], v[96:99]
	v_mfma_f32_16x16x32_bf16 v[84:87], v[208:211], v[192:195], v[84:87]
	v_mfma_f32_16x16x32_bf16 v[80:83], v[216:219], v[192:195], v[80:83]
	v_mfma_f32_16x16x32_bf16 v[68:71], v[208:211], v[200:203], v[68:71]
	v_mfma_f32_16x16x32_bf16 v[64:67], v[216:219], v[200:203], v[64:67]
	v_mfma_f32_16x16x32_bf16 v[116:119], v[212:215], v[168:171], v[116:119]
	v_mfma_f32_16x16x32_bf16 v[112:115], v[220:223], v[168:171], v[112:115]
	v_mfma_f32_16x16x32_bf16 v[100:103], v[212:215], v[188:191], v[100:103]
	v_mfma_f32_16x16x32_bf16 v[96:99], v[220:223], v[188:191], v[96:99]
	v_mfma_f32_16x16x32_bf16 v[84:87], v[212:215], v[196:199], v[84:87]
	v_mfma_f32_16x16x32_bf16 v[80:83], v[220:223], v[196:199], v[80:83]
	v_mfma_f32_16x16x32_bf16 v[68:71], v[212:215], v[204:207], v[68:71]
	v_mfma_f32_16x16x32_bf16 v[64:67], v[220:223], v[204:207], v[64:67]
	s_barrier
	s_setprio 0
	s_add_i32 s0, s17, s45
	v_lshl_add_u64 v[224:225], s[34:35], 0, v[154:155]
	s_mov_b32 m0, s0
	global_load_lds_dwordx4 v[224:225], off
	v_lshl_add_u64 v[226:227], s[34:35], 0, v[128:129]
	s_add_i32 m0, s0, 0x2000
	s_nop 0
	global_load_lds_dwordx4 v[226:227], off
	s_mov_b32 m0, s39
	v_lshl_add_u64 v[228:229], s[42:43], 0, v[132:133]
	ds_read_b128 v[164:167], v145 offset:16384
	ds_read_b128 v[168:171], v145 offset:17408
	ds_read_b128 v[184:187], v145 offset:18432
	ds_read_b128 v[188:191], v145 offset:19456
	ds_read_b128 v[192:195], v145 offset:20480
	ds_read_b128 v[196:199], v145 offset:21504
	ds_read_b128 v[200:203], v145 offset:22528
	ds_read_b128 v[204:207], v145 offset:23552
	global_load_lds_dwordx4 v[228:229], off
	v_lshl_add_u64 v[230:231], s[42:43], 0, v[130:131]
	s_mov_b32 m0, s47
	s_nop 0
	global_load_lds_dwordx4 v[230:231], off
	s_add_u32 s0, s34, 0x40000
	s_addc_u32 s1, s35, 0
	s_add_i32 s17, s63, s45
	v_lshl_add_u64 v[238:239], s[0:1], 0, v[154:155]
	s_mov_b32 m0, s17
	s_nop 0
	global_load_lds_dwordx4 v[238:239], off
	v_lshl_add_u64 v[238:239], s[0:1], 0, v[128:129]
	s_add_i32 m0, s17, 0x2000
	s_nop 0
	global_load_lds_dwordx4 v[238:239], off
	s_waitcnt vmcnt(6)
	s_waitcnt lgkmcnt(0)
	s_setprio 1
	s_barrier
	v_mfma_f32_16x16x32_bf16 v[60:63], v[138:141], v[164:167], v[60:63]
	v_mfma_f32_16x16x32_bf16 v[56:59], v[150:153], v[164:167], v[56:59]
	v_mfma_f32_16x16x32_bf16 v[44:47], v[138:141], v[184:187], v[44:47]
	s_add_i32 s17, 0, 0x18000
	v_mfma_f32_16x16x32_bf16 v[40:43], v[150:153], v[184:187], v[40:43]
	v_add_u32_e32 v241, s17, v143
	v_mfma_f32_16x16x32_bf16 v[28:31], v[138:141], v[192:195], v[28:31]
	v_mfma_f32_16x16x32_bf16 v[24:27], v[150:153], v[192:195], v[24:27]
	v_mfma_f32_16x16x32_bf16 v[12:15], v[138:141], v[200:203], v[12:15]
	v_mfma_f32_16x16x32_bf16 v[8:11], v[150:153], v[200:203], v[8:11]
	v_mfma_f32_16x16x32_bf16 v[60:63], v[146:149], v[168:171], v[60:63]
	v_mfma_f32_16x16x32_bf16 v[56:59], v[160:163], v[168:171], v[56:59]
	v_mfma_f32_16x16x32_bf16 v[44:47], v[146:149], v[188:191], v[44:47]
	v_mfma_f32_16x16x32_bf16 v[40:43], v[160:163], v[188:191], v[40:43]
	v_mfma_f32_16x16x32_bf16 v[28:31], v[146:149], v[196:199], v[28:31]
	v_mfma_f32_16x16x32_bf16 v[24:27], v[160:163], v[196:199], v[24:27]
	v_mfma_f32_16x16x32_bf16 v[12:15], v[146:149], v[204:207], v[12:15]
	v_mfma_f32_16x16x32_bf16 v[8:11], v[160:163], v[204:207], v[8:11]
	v_mfma_f32_16x16x32_bf16 v[52:55], v[208:211], v[164:167], v[52:55]
	v_mfma_f32_16x16x32_bf16 v[48:51], v[216:219], v[164:167], v[48:51]
	v_mfma_f32_16x16x32_bf16 v[36:39], v[208:211], v[184:187], v[36:39]
	v_mfma_f32_16x16x32_bf16 v[32:35], v[216:219], v[184:187], v[32:35]
	v_mfma_f32_16x16x32_bf16 v[20:23], v[208:211], v[192:195], v[20:23]
	v_mfma_f32_16x16x32_bf16 v[16:19], v[216:219], v[192:195], v[16:19]
	v_mfma_f32_16x16x32_bf16 v[4:7], v[208:211], v[200:203], v[4:7]
	v_mfma_f32_16x16x32_bf16 v[0:3], v[216:219], v[200:203], v[0:3]
	v_mfma_f32_16x16x32_bf16 v[52:55], v[212:215], v[168:171], v[52:55]
	v_mfma_f32_16x16x32_bf16 v[48:51], v[220:223], v[168:171], v[48:51]
	v_mfma_f32_16x16x32_bf16 v[36:39], v[212:215], v[188:191], v[36:39]
	v_mfma_f32_16x16x32_bf16 v[32:35], v[220:223], v[188:191], v[32:35]
	v_mfma_f32_16x16x32_bf16 v[20:23], v[212:215], v[196:199], v[20:23]
	v_mfma_f32_16x16x32_bf16 v[16:19], v[220:223], v[196:199], v[16:19]
	v_mfma_f32_16x16x32_bf16 v[4:7], v[212:215], v[204:207], v[4:7]
	v_mfma_f32_16x16x32_bf16 v[0:3], v[220:223], v[204:207], v[0:3]
	s_barrier
; #define PG8_STAGE(bufoff, gbase, voff) do { _Pragma("unroll") for (int _i = 0; _i < 2; ++_i) \
;         __builtin_amdgcn_global_load_lds((const unsigned*)((const char*)(gbase) + (voff)[_i]), (LAS unsigned*)(lds + (bufoff) + ldsw + _i * 8192), 16, 0, 0); } while (0)
; #define PG8_LDA(dst, b, h) do { _Pragma("unroll") for (int m = 0; m < 4; ++m) _Pragma("unroll") for (int k = 0; k < 2; ++k) dst[m][k] = *(const LAS bf16x8*)(lds + PG8_SA(b, h) + aoff + m * 2048 + k * 1024); } while (0)
; #define PG8_LDB(dst, b, h) do { _Pragma("unroll") for (int n = 0; n < 2; ++n) _Pragma("unroll") for (int k = 0; k < 2; ++k) dst[n][k] = *(const LAS bf16x8*)(lds + PG8_SB(b, h) + boff + n * 2048 + k * 1024); } while (0)
; #define PG8_MMA(ai, bj, At, Bt) do { __builtin_amdgcn_s_setprio(1); _Pragma("unroll") for (int m = 0; m < 4; ++m) _Pragma("unroll") for (int n = 0; n < 2; ++n) _Pragma("unroll") for (int k = 0; k < 2; ++k) \
;         acc[ai][bj][m][n] = __builtin_amdgcn_mfma_f32_16x16x32_bf16(Bt[n][k], At[m][k], acc[ai][bj][m][n], 0, 0, 0); __builtin_amdgcn_s_setprio(0); } while (0)
; #define PG8_WAIT_V(n) asm volatile("s_waitcnt vmcnt(" #n ")" ::: "memory")
; #define PG8_WAIT_L(n) asm volatile("s_waitcnt lgkmcnt(" #n ")" ::: "memory")
; #define PG8_BAR __builtin_amdgcn_s_barrier()
; #define PG8_SCHED __builtin_amdgcn_sched_barrier(0)
; template <class Epi, class Sched>
; __device__ __forceinline__ void gemm_phase(LAS unsigned char* lds, const Gemm g, const Sched& S, const Epi& E, int tid) {
;     ...
;             PG8_LDB(B0, 1, 0); PG8_SCHED; PG8_LDA(At, 1, 0); PG8_STAGE(PG8_SA(0, 1), a2 + hstep, voffA);
;             PG8_WAIT_L(8); PG8_BAR; PG8_WAIT_L(0); PG8_MMA(0, 0, At, B0); PG8_BAR; PG8_SCHED;
;             PG8_LDB(B1, 1, 1); PG8_STAGE(PG8_SB(1, 0), b3, voffB);
;             PG8_BAR; PG8_WAIT_L(0); PG8_MMA(0, 1, At, B1); PG8_BAR;
;             PG8_LDA(At, 1, 1); PG8_STAGE(PG8_SA(1, 0), a3, voffA);
;             PG8_BAR; PG8_WAIT_L(0); PG8_MMA(1, 0, At, B0); PG8_BAR; PG8_SCHED;
;             PG8_STAGE(PG8_SB(1, 1), b3 + hstep, voffB);
;             PG8_WAIT_V(6); PG8_BAR; PG8_MMA(1, 1, At, B1); PG8_BAR;
	s_setprio 0
	ds_read_b128 v[138:141], v241
	ds_read_b128 v[146:149], v241 offset:1024
	ds_read_b128 v[150:153], v241 offset:2048
	ds_read_b128 v[160:163], v241 offset:3072
	s_add_u32 s0, s42, 0x40000
	s_addc_u32 s1, s43, 0
	s_mov_b32 m0, s48
	v_lshl_add_u64 v[208:209], s[0:1], 0, v[132:133]
	ds_read_b128 v[164:167], v145 offset:32768
	ds_read_b128 v[168:171], v145 offset:33792
	ds_read_b128 v[184:187], v145 offset:34816
	ds_read_b128 v[188:191], v145 offset:35840
	ds_read_b128 v[192:195], v145 offset:36864
	ds_read_b128 v[196:199], v145 offset:37888
	ds_read_b128 v[200:203], v145 offset:38912
	ds_read_b128 v[204:207], v145 offset:39936
	global_load_lds_dwordx4 v[208:209], off
	v_lshl_add_u64 v[208:209], s[0:1], 0, v[130:131]
	s_mov_b32 m0, s49
	s_nop 0
	global_load_lds_dwordx4 v[208:209], off
	s_add_i32 s42, 0, 0x1c000
	v_add_u32_e32 v183, s42, v143
	ds_read_b128 v[208:211], v183
	ds_read_b128 v[212:215], v183 offset:1024
	ds_read_b128 v[216:219], v183 offset:2048
	ds_read_b128 v[220:223], v183 offset:3072
	s_waitcnt lgkmcnt(0)
	s_setprio 1
	s_barrier
	v_mfma_f32_16x16x32_bf16 v[124:127], v[138:141], v[164:167], v[124:127]
	v_mfma_f32_16x16x32_bf16 v[120:123], v[150:153], v[164:167], v[120:123]
	v_mfma_f32_16x16x32_bf16 v[108:111], v[138:141], v[184:187], v[108:111]
	v_mfma_f32_16x16x32_bf16 v[104:107], v[150:153], v[184:187], v[104:107]
	v_mfma_f32_16x16x32_bf16 v[92:95], v[138:141], v[192:195], v[92:95]
	v_mfma_f32_16x16x32_bf16 v[88:91], v[150:153], v[192:195], v[88:91]
	v_mfma_f32_16x16x32_bf16 v[76:79], v[138:141], v[200:203], v[76:79]
	v_mfma_f32_16x16x32_bf16 v[72:75], v[150:153], v[200:203], v[72:75]
	v_mfma_f32_16x16x32_bf16 v[124:127], v[146:149], v[168:171], v[124:127]
	v_mfma_f32_16x16x32_bf16 v[120:123], v[160:163], v[168:171], v[120:123]
	v_mfma_f32_16x16x32_bf16 v[108:111], v[146:149], v[188:191], v[108:111]
	v_mfma_f32_16x16x32_bf16 v[104:107], v[160:163], v[188:191], v[104:107]
	v_mfma_f32_16x16x32_bf16 v[92:95], v[146:149], v[196:199], v[92:95]
	v_mfma_f32_16x16x32_bf16 v[88:91], v[160:163], v[196:199], v[88:91]
	v_mfma_f32_16x16x32_bf16 v[76:79], v[146:149], v[204:207], v[76:79]
	v_mfma_f32_16x16x32_bf16 v[72:75], v[160:163], v[204:207], v[72:75]
	v_mfma_f32_16x16x32_bf16 v[116:119], v[208:211], v[164:167], v[116:119]
	v_mfma_f32_16x16x32_bf16 v[112:115], v[216:219], v[164:167], v[112:115]
	v_mfma_f32_16x16x32_bf16 v[100:103], v[208:211], v[184:187], v[100:103]
	v_mfma_f32_16x16x32_bf16 v[96:99], v[216:219], v[184:187], v[96:99]
	v_mfma_f32_16x16x32_bf16 v[84:87], v[208:211], v[192:195], v[84:87]
	v_mfma_f32_16x16x32_bf16 v[80:83], v[216:219], v[192:195], v[80:83]
	v_mfma_f32_16x16x32_bf16 v[68:71], v[208:211], v[200:203], v[68:71]
	v_mfma_f32_16x16x32_bf16 v[64:67], v[216:219], v[200:203], v[64:67]
	v_mfma_f32_16x16x32_bf16 v[116:119], v[212:215], v[168:171], v[116:119]
	v_mfma_f32_16x16x32_bf16 v[112:115], v[220:223], v[168:171], v[112:115]
	v_mfma_f32_16x16x32_bf16 v[100:103], v[212:215], v[188:191], v[100:103]
	v_mfma_f32_16x16x32_bf16 v[96:99], v[220:223], v[188:191], v[96:99]
	v_mfma_f32_16x16x32_bf16 v[84:87], v[212:215], v[196:199], v[84:87]
	v_mfma_f32_16x16x32_bf16 v[80:83], v[220:223], v[196:199], v[80:83]
	v_mfma_f32_16x16x32_bf16 v[68:71], v[212:215], v[204:207], v[68:71]
	v_mfma_f32_16x16x32_bf16 v[64:67], v[220:223], v[204:207], v[64:67]
	s_barrier
	s_setprio 0
	s_add_i32 s0, s17, s45
	v_lshl_add_u64 v[224:225], v[224:225], 0, s[8:9]
	s_mov_b32 m0, s0
	global_load_lds_dwordx4 v[224:225], off
	v_lshl_add_u64 v[224:225], v[226:227], 0, s[8:9]
	s_add_i32 m0, s0, 0x2000
	s_nop 0
	global_load_lds_dwordx4 v[224:225], off
	s_mov_b32 m0, s6
	v_lshl_add_u64 v[224:225], v[228:229], 0, s[8:9]
	ds_read_b128 v[164:167], v145 offset:49152
	ds_read_b128 v[168:171], v145 offset:50176
	ds_read_b128 v[184:187], v145 offset:51200
	ds_read_b128 v[188:191], v145 offset:52224
	ds_read_b128 v[192:195], v145 offset:53248
	ds_read_b128 v[196:199], v145 offset:54272
	ds_read_b128 v[200:203], v145 offset:55296
	ds_read_b128 v[204:207], v145 offset:56320
	global_load_lds_dwordx4 v[224:225], off
	v_lshl_add_u64 v[224:225], v[230:231], 0, s[8:9]
	s_mov_b32 m0, s50
	s_nop 0
	global_load_lds_dwordx4 v[224:225], off
	s_add_u32 s0, s34, 0x40080
	s_addc_u32 s1, s35, 0
	s_add_i32 s17, s42, s45
	v_lshl_add_u64 v[238:239], s[0:1], 0, v[154:155]
	s_mov_b32 m0, s17
	s_nop 0
	global_load_lds_dwordx4 v[238:239], off
	v_lshl_add_u64 v[238:239], s[0:1], 0, v[128:129]
	s_add_i32 m0, s17, 0x2000
	s_nop 0
	global_load_lds_dwordx4 v[238:239], off
	s_waitcnt vmcnt(6)
	s_waitcnt lgkmcnt(0)
	s_setprio 1
	s_barrier
	v_mfma_f32_16x16x32_bf16 v[60:63], v[138:141], v[164:167], v[60:63]
	v_mfma_f32_16x16x32_bf16 v[56:59], v[150:153], v[164:167], v[56:59]
	v_mfma_f32_16x16x32_bf16 v[44:47], v[138:141], v[184:187], v[44:47]
	s_add_i32 s61, s61, 2
	v_mfma_f32_16x16x32_bf16 v[40:43], v[150:153], v[184:187], v[40:43]
	s_add_u32 s40, s40, 0x100
	v_mfma_f32_16x16x32_bf16 v[28:31], v[138:141], v[192:195], v[28:31]
	s_addc_u32 s41, s41, 0
	v_mfma_f32_16x16x32_bf16 v[24:27], v[150:153], v[192:195], v[24:27]
	s_add_u32 s58, s58, 0x100
	v_mfma_f32_16x16x32_bf16 v[12:15], v[138:141], v[200:203], v[12:15]
	s_addc_u32 s60, s60, 0
	v_mfma_f32_16x16x32_bf16 v[8:11], v[150:153], v[200:203], v[8:11]
	s_cmp_gt_u32 s61, 13
	v_mfma_f32_16x16x32_bf16 v[60:63], v[146:149], v[168:171], v[60:63]
	v_mfma_f32_16x16x32_bf16 v[56:59], v[160:163], v[168:171], v[56:59]
	v_mfma_f32_16x16x32_bf16 v[44:47], v[146:149], v[188:191], v[44:47]
	v_mfma_f32_16x16x32_bf16 v[40:43], v[160:163], v[188:191], v[40:43]
	v_mfma_f32_16x16x32_bf16 v[28:31], v[146:149], v[196:199], v[28:31]
	v_mfma_f32_16x16x32_bf16 v[24:27], v[160:163], v[196:199], v[24:27]
	v_mfma_f32_16x16x32_bf16 v[12:15], v[146:149], v[204:207], v[12:15]
	v_mfma_f32_16x16x32_bf16 v[8:11], v[160:163], v[204:207], v[8:11]
	v_mfma_f32_16x16x32_bf16 v[52:55], v[208:211], v[164:167], v[52:55]
	v_mfma_f32_16x16x32_bf16 v[48:51], v[216:219], v[164:167], v[48:51]
	v_mfma_f32_16x16x32_bf16 v[36:39], v[208:211], v[184:187], v[36:39]
	v_mfma_f32_16x16x32_bf16 v[32:35], v[216:219], v[184:187], v[32:35]
	v_mfma_f32_16x16x32_bf16 v[20:23], v[208:211], v[192:195], v[20:23]
	v_mfma_f32_16x16x32_bf16 v[16:19], v[216:219], v[192:195], v[16:19]
	v_mfma_f32_16x16x32_bf16 v[4:7], v[208:211], v[200:203], v[4:7]
	v_mfma_f32_16x16x32_bf16 v[0:3], v[216:219], v[200:203], v[0:3]
	v_mfma_f32_16x16x32_bf16 v[52:55], v[212:215], v[168:171], v[52:55]
	v_mfma_f32_16x16x32_bf16 v[48:51], v[220:223], v[168:171], v[48:51]
	v_mfma_f32_16x16x32_bf16 v[36:39], v[212:215], v[188:191], v[36:39]
	v_mfma_f32_16x16x32_bf16 v[32:35], v[220:223], v[188:191], v[32:35]
	v_mfma_f32_16x16x32_bf16 v[20:23], v[212:215], v[196:199], v[20:23]
	v_mfma_f32_16x16x32_bf16 v[16:19], v[220:223], v[196:199], v[16:19]
	v_mfma_f32_16x16x32_bf16 v[4:7], v[212:215], v[204:207], v[4:7]
	v_mfma_f32_16x16x32_bf16 v[0:3], v[220:223], v[204:207], v[0:3]
	s_barrier
	s_setprio 0
	s_cbranch_scc0 .LBB0_115
